# v47 + w_proj_a transposes moved from phase 4 into the ra_items tail of workgroups 32..255 (3 items per wave)
# baseline (speedup 1.0000x reference)
.LBB0_402:
	v_readlane_b32 s94, v254, 0
	v_readfirstlane_b32 s95, v0
	s_nop 3
	s_cmpk_lt_u32 s94, 0x20
	s_cbranch_scc1 .Lwa_done
	s_lshr_b32 s95, s95, 6
	s_sub_u32 s94, s94, 0x20
	s_lshl_b32 s94, s94, 3
	s_add_u32 s94, s94, s95
	s_waitcnt lgkmcnt(0)
	s_barrier
	v_readlane_b32 s96, v254, 2
	v_readlane_b32 s97, v254, 3
	s_nop 3
	s_sub_u32 s96, s96, 0x68
	s_subb_u32 s97, s97, 0
	s_load_dwordx2 s[100:101], s[96:97], 0x0
	v_and_b32_e32 v2, 63, v0
	v_lshrrev_b32_e32 v3, 3, v2
	v_and_b32_e32 v4, 7, v2
	v_lshlrev_b32_e32 v5, 14, v3
	v_lshl_add_u32 v5, v4, 4, v5
	v_add_u32_e32 v6, 0x0, v5
	v_add_u32_e32 v7, 0x20000, v5
	v_add_u32_e32 v8, 0x40000, v5
	v_add_u32_e32 v9, 0x60000, v5
	v_add_u32_e32 v10, 0x80000, v5
	v_add_u32_e32 v11, 0xa0000, v5
	v_add_u32_e32 v12, 0xc0000, v5
	v_add_u32_e32 v13, 0xe0000, v5
	s_lshl_b32 s95, s95, 14
	v_mul_u32_u24_e32 v14, 0x84, v3
	v_lshl_add_u32 v14, v4, 4, v14
	v_add_u32_e32 v14, s95, v14
	v_mul_u32_u24_e32 v15, 0x420, v4
	v_lshl_add_u32 v15, v3, 2, v15
	v_add_u32_e32 v15, s95, v15
	v_mul_u32_u24_e32 v16, 0x1000, v3
	v_lshl_add_u32 v16, v4, 4, v16
	v_add_u32_e32 v17, 0x8000, v16
	v_add_u32_e32 v18, 0x10000, v16
	v_add_u32_e32 v19, 0x18000, v16
	s_waitcnt lgkmcnt(0)
	s_mov_b32 s95, s94
	s_min_u32 s95, s95, 0xfff
	s_lshr_b32 vcc_lo, s95, 7
	s_and_b32 vcc_hi, s95, 0x7f
	s_lshl_b32 vcc_lo, vcc_lo, 20
	s_lshl_b32 vcc_hi, vcc_hi, 7
	s_add_u32 s96, s100, vcc_lo
	s_addc_u32 s97, s101, 0
	s_add_u32 s96, s96, vcc_hi
	s_addc_u32 s97, s97, 0
	global_load_dwordx4 v[20:23], v6, s[96:97]
	global_load_dwordx4 v[24:27], v7, s[96:97]
	global_load_dwordx4 v[28:31], v8, s[96:97]
	global_load_dwordx4 v[32:35], v9, s[96:97]
	global_load_dwordx4 v[36:39], v10, s[96:97]
	global_load_dwordx4 v[40:43], v11, s[96:97]
	global_load_dwordx4 v[44:47], v12, s[96:97]
	global_load_dwordx4 v[48:51], v13, s[96:97]
	s_add_u32 s95, s94, 0x700
	s_min_u32 s95, s95, 0xfff
	s_lshr_b32 vcc_lo, s95, 7
	s_and_b32 vcc_hi, s95, 0x7f
	s_lshl_b32 vcc_lo, vcc_lo, 20
	s_lshl_b32 vcc_hi, vcc_hi, 7
	s_add_u32 s96, s100, vcc_lo
	s_addc_u32 s97, s101, 0
	s_add_u32 s96, s96, vcc_hi
	s_addc_u32 s97, s97, 0
	global_load_dwordx4 v[100:103], v6, s[96:97]
	global_load_dwordx4 v[104:107], v7, s[96:97]
	global_load_dwordx4 v[108:111], v8, s[96:97]
	global_load_dwordx4 v[112:115], v9, s[96:97]
	global_load_dwordx4 v[116:119], v10, s[96:97]
	global_load_dwordx4 v[120:123], v11, s[96:97]
	global_load_dwordx4 v[124:127], v12, s[96:97]
	global_load_dwordx4 v[128:131], v13, s[96:97]
	s_waitcnt vmcnt(15)
	ds_write_b32 v14, v20 offset:0
	ds_write_b32 v14, v21 offset:4
	ds_write_b32 v14, v22 offset:8
	ds_write_b32 v14, v23 offset:12
	s_waitcnt vmcnt(14)
	ds_write_b32 v14, v24 offset:1056
	ds_write_b32 v14, v25 offset:1060
	ds_write_b32 v14, v26 offset:1064
	ds_write_b32 v14, v27 offset:1068
	s_waitcnt vmcnt(13)
	ds_write_b32 v14, v28 offset:2112
	ds_write_b32 v14, v29 offset:2116
	ds_write_b32 v14, v30 offset:2120
	ds_write_b32 v14, v31 offset:2124
	s_waitcnt vmcnt(12)
	ds_write_b32 v14, v32 offset:3168
	ds_write_b32 v14, v33 offset:3172
	ds_write_b32 v14, v34 offset:3176
	ds_write_b32 v14, v35 offset:3180
	s_waitcnt vmcnt(11)
	ds_write_b32 v14, v36 offset:4224
	ds_write_b32 v14, v37 offset:4228
	ds_write_b32 v14, v38 offset:4232
	ds_write_b32 v14, v39 offset:4236
	s_waitcnt vmcnt(10)
	ds_write_b32 v14, v40 offset:5280
	ds_write_b32 v14, v41 offset:5284
	ds_write_b32 v14, v42 offset:5288
	ds_write_b32 v14, v43 offset:5292
	s_waitcnt vmcnt(9)
	ds_write_b32 v14, v44 offset:6336
	ds_write_b32 v14, v45 offset:6340
	ds_write_b32 v14, v46 offset:6344
	ds_write_b32 v14, v47 offset:6348
	s_waitcnt vmcnt(8)
	ds_write_b32 v14, v48 offset:7392
	ds_write_b32 v14, v49 offset:7396
	ds_write_b32 v14, v50 offset:7400
	ds_write_b32 v14, v51 offset:7404
	s_add_u32 s95, s94, 0xe00
	s_min_u32 s95, s95, 0xfff
	s_lshr_b32 vcc_lo, s95, 7
	s_and_b32 vcc_hi, s95, 0x7f
	s_lshl_b32 vcc_lo, vcc_lo, 20
	s_lshl_b32 vcc_hi, vcc_hi, 7
	s_add_u32 s96, s100, vcc_lo
	s_addc_u32 s97, s101, 0
	s_add_u32 s96, s96, vcc_hi
	s_addc_u32 s97, s97, 0
	global_load_dwordx4 v[20:23], v6, s[96:97]
	global_load_dwordx4 v[24:27], v7, s[96:97]
	global_load_dwordx4 v[28:31], v8, s[96:97]
	global_load_dwordx4 v[32:35], v9, s[96:97]
	global_load_dwordx4 v[36:39], v10, s[96:97]
	global_load_dwordx4 v[40:43], v11, s[96:97]
	global_load_dwordx4 v[44:47], v12, s[96:97]
	global_load_dwordx4 v[48:51], v13, s[96:97]
	ds_read2_b32 v[52:53], v15 offset0:0 offset1:33
	ds_read2_b32 v[54:55], v15 offset0:66 offset1:99
	ds_read2_b32 v[56:57], v15 offset0:132 offset1:165
	ds_read2_b32 v[58:59], v15 offset0:198 offset1:231
	ds_read2_b32 v[60:61], v15 offset0:8 offset1:41
	ds_read2_b32 v[62:63], v15 offset0:74 offset1:107
	ds_read2_b32 v[64:65], v15 offset0:140 offset1:173
	ds_read2_b32 v[66:67], v15 offset0:206 offset1:239
	ds_read2_b32 v[68:69], v15 offset0:16 offset1:49
	ds_read2_b32 v[70:71], v15 offset0:82 offset1:115
	ds_read2_b32 v[72:73], v15 offset0:148 offset1:181
	ds_read2_b32 v[74:75], v15 offset0:214 offset1:247
	ds_read2_b32 v[76:77], v15 offset0:24 offset1:57
	ds_read2_b32 v[78:79], v15 offset0:90 offset1:123
	ds_read2_b32 v[80:81], v15 offset0:156 offset1:189
	ds_read2_b32 v[82:83], v15 offset0:222 offset1:255
	s_mov_b32 s95, s94
	s_min_u32 s95, s95, 0xfff
	s_lshr_b32 vcc_lo, s95, 7
	s_and_b32 vcc_hi, s95, 0x7f
	s_mul_i32 vcc_hi, vcc_hi, 0x20000
	s_lshl_b32 vcc_lo, vcc_lo, 7
	s_add_u32 s98, s66, 0x4100000
	s_addc_u32 s99, s67, 0
	s_add_u32 s98, s98, vcc_hi
	s_addc_u32 s99, s99, 0
	s_add_u32 s98, s98, vcc_lo
	s_addc_u32 s99, s99, 0
	s_waitcnt lgkmcnt(0)
	v_cvt_pk_bf16_f32 v84, v52, v53
	v_cvt_pk_bf16_f32 v85, v54, v55
	v_cvt_pk_bf16_f32 v86, v56, v57
	v_cvt_pk_bf16_f32 v87, v58, v59
	v_cvt_pk_bf16_f32 v88, v60, v61
	v_cvt_pk_bf16_f32 v89, v62, v63
	v_cvt_pk_bf16_f32 v90, v64, v65
	v_cvt_pk_bf16_f32 v91, v66, v67
	v_cvt_pk_bf16_f32 v92, v68, v69
	v_cvt_pk_bf16_f32 v93, v70, v71
	v_cvt_pk_bf16_f32 v94, v72, v73
	v_cvt_pk_bf16_f32 v95, v74, v75
	v_cvt_pk_bf16_f32 v96, v76, v77
	v_cvt_pk_bf16_f32 v97, v78, v79
	v_cvt_pk_bf16_f32 v98, v80, v81
	v_cvt_pk_bf16_f32 v99, v82, v83
	global_store_dwordx4 v16, v[84:87], s[98:99]
	global_store_dwordx4 v17, v[88:91], s[98:99]
	global_store_dwordx4 v18, v[92:95], s[98:99]
	global_store_dwordx4 v19, v[96:99], s[98:99]
	s_waitcnt vmcnt(19)
	ds_write_b32 v14, v100 offset:0
	ds_write_b32 v14, v101 offset:4
	ds_write_b32 v14, v102 offset:8
	ds_write_b32 v14, v103 offset:12
	s_waitcnt vmcnt(18)
	ds_write_b32 v14, v104 offset:1056
	ds_write_b32 v14, v105 offset:1060
	ds_write_b32 v14, v106 offset:1064
	ds_write_b32 v14, v107 offset:1068
	s_waitcnt vmcnt(17)
	ds_write_b32 v14, v108 offset:2112
	ds_write_b32 v14, v109 offset:2116
	ds_write_b32 v14, v110 offset:2120
	ds_write_b32 v14, v111 offset:2124
	s_waitcnt vmcnt(16)
	ds_write_b32 v14, v112 offset:3168
	ds_write_b32 v14, v113 offset:3172
	ds_write_b32 v14, v114 offset:3176
	ds_write_b32 v14, v115 offset:3180
	s_waitcnt vmcnt(15)
	ds_write_b32 v14, v116 offset:4224
	ds_write_b32 v14, v117 offset:4228
	ds_write_b32 v14, v118 offset:4232
	ds_write_b32 v14, v119 offset:4236
	s_waitcnt vmcnt(14)
	ds_write_b32 v14, v120 offset:5280
	ds_write_b32 v14, v121 offset:5284
	ds_write_b32 v14, v122 offset:5288
	ds_write_b32 v14, v123 offset:5292
	s_waitcnt vmcnt(13)
	ds_write_b32 v14, v124 offset:6336
	ds_write_b32 v14, v125 offset:6340
	ds_write_b32 v14, v126 offset:6344
	ds_write_b32 v14, v127 offset:6348
	s_waitcnt vmcnt(12)
	ds_write_b32 v14, v128 offset:7392
	ds_write_b32 v14, v129 offset:7396
	ds_write_b32 v14, v130 offset:7400
	ds_write_b32 v14, v131 offset:7404
	ds_read2_b32 v[52:53], v15 offset0:0 offset1:33
	ds_read2_b32 v[54:55], v15 offset0:66 offset1:99
	ds_read2_b32 v[56:57], v15 offset0:132 offset1:165
	ds_read2_b32 v[58:59], v15 offset0:198 offset1:231
	ds_read2_b32 v[60:61], v15 offset0:8 offset1:41
	ds_read2_b32 v[62:63], v15 offset0:74 offset1:107
	ds_read2_b32 v[64:65], v15 offset0:140 offset1:173
	ds_read2_b32 v[66:67], v15 offset0:206 offset1:239
	ds_read2_b32 v[68:69], v15 offset0:16 offset1:49
	ds_read2_b32 v[70:71], v15 offset0:82 offset1:115
	ds_read2_b32 v[72:73], v15 offset0:148 offset1:181
	ds_read2_b32 v[74:75], v15 offset0:214 offset1:247
	ds_read2_b32 v[76:77], v15 offset0:24 offset1:57
	ds_read2_b32 v[78:79], v15 offset0:90 offset1:123
	ds_read2_b32 v[80:81], v15 offset0:156 offset1:189
	ds_read2_b32 v[82:83], v15 offset0:222 offset1:255
	s_add_u32 s95, s94, 0x700
	s_min_u32 s95, s95, 0xfff
	s_lshr_b32 vcc_lo, s95, 7
	s_and_b32 vcc_hi, s95, 0x7f
	s_mul_i32 vcc_hi, vcc_hi, 0x20000
	s_lshl_b32 vcc_lo, vcc_lo, 7
	s_add_u32 s98, s66, 0x4100000
	s_addc_u32 s99, s67, 0
	s_add_u32 s98, s98, vcc_hi
	s_addc_u32 s99, s99, 0
	s_add_u32 s98, s98, vcc_lo
	s_addc_u32 s99, s99, 0
	s_waitcnt lgkmcnt(0)
	v_cvt_pk_bf16_f32 v84, v52, v53
	v_cvt_pk_bf16_f32 v85, v54, v55
	v_cvt_pk_bf16_f32 v86, v56, v57
	v_cvt_pk_bf16_f32 v87, v58, v59
	v_cvt_pk_bf16_f32 v88, v60, v61
	v_cvt_pk_bf16_f32 v89, v62, v63
	v_cvt_pk_bf16_f32 v90, v64, v65
	v_cvt_pk_bf16_f32 v91, v66, v67
	v_cvt_pk_bf16_f32 v92, v68, v69
	v_cvt_pk_bf16_f32 v93, v70, v71
	v_cvt_pk_bf16_f32 v94, v72, v73
	v_cvt_pk_bf16_f32 v95, v74, v75
	v_cvt_pk_bf16_f32 v96, v76, v77
	v_cvt_pk_bf16_f32 v97, v78, v79
	v_cvt_pk_bf16_f32 v98, v80, v81
	v_cvt_pk_bf16_f32 v99, v82, v83
	global_store_dwordx4 v16, v[84:87], s[98:99]
	global_store_dwordx4 v17, v[88:91], s[98:99]
	global_store_dwordx4 v18, v[92:95], s[98:99]
	global_store_dwordx4 v19, v[96:99], s[98:99]
	s_waitcnt vmcnt(15)
	ds_write_b32 v14, v20 offset:0
	ds_write_b32 v14, v21 offset:4
	ds_write_b32 v14, v22 offset:8
	ds_write_b32 v14, v23 offset:12
	s_waitcnt vmcnt(14)
	ds_write_b32 v14, v24 offset:1056
	ds_write_b32 v14, v25 offset:1060
	ds_write_b32 v14, v26 offset:1064
	ds_write_b32 v14, v27 offset:1068
	s_waitcnt vmcnt(13)
	ds_write_b32 v14, v28 offset:2112
	ds_write_b32 v14, v29 offset:2116
	ds_write_b32 v14, v30 offset:2120
	ds_write_b32 v14, v31 offset:2124
	s_waitcnt vmcnt(12)
	ds_write_b32 v14, v32 offset:3168
	ds_write_b32 v14, v33 offset:3172
	ds_write_b32 v14, v34 offset:3176
	ds_write_b32 v14, v35 offset:3180
	s_waitcnt vmcnt(11)
	ds_write_b32 v14, v36 offset:4224
	ds_write_b32 v14, v37 offset:4228
	ds_write_b32 v14, v38 offset:4232
	ds_write_b32 v14, v39 offset:4236
	s_waitcnt vmcnt(10)
	ds_write_b32 v14, v40 offset:5280
	ds_write_b32 v14, v41 offset:5284
	ds_write_b32 v14, v42 offset:5288
	ds_write_b32 v14, v43 offset:5292
	s_waitcnt vmcnt(9)
	ds_write_b32 v14, v44 offset:6336
	ds_write_b32 v14, v45 offset:6340
	ds_write_b32 v14, v46 offset:6344
	ds_write_b32 v14, v47 offset:6348
	s_waitcnt vmcnt(8)
	ds_write_b32 v14, v48 offset:7392
	ds_write_b32 v14, v49 offset:7396
	ds_write_b32 v14, v50 offset:7400
	ds_write_b32 v14, v51 offset:7404
	ds_read2_b32 v[52:53], v15 offset0:0 offset1:33
	ds_read2_b32 v[54:55], v15 offset0:66 offset1:99
	ds_read2_b32 v[56:57], v15 offset0:132 offset1:165
	ds_read2_b32 v[58:59], v15 offset0:198 offset1:231
	ds_read2_b32 v[60:61], v15 offset0:8 offset1:41
	ds_read2_b32 v[62:63], v15 offset0:74 offset1:107
	ds_read2_b32 v[64:65], v15 offset0:140 offset1:173
	ds_read2_b32 v[66:67], v15 offset0:206 offset1:239
	ds_read2_b32 v[68:69], v15 offset0:16 offset1:49
	ds_read2_b32 v[70:71], v15 offset0:82 offset1:115
	ds_read2_b32 v[72:73], v15 offset0:148 offset1:181
	ds_read2_b32 v[74:75], v15 offset0:214 offset1:247
	ds_read2_b32 v[76:77], v15 offset0:24 offset1:57
	ds_read2_b32 v[78:79], v15 offset0:90 offset1:123
	ds_read2_b32 v[80:81], v15 offset0:156 offset1:189
	ds_read2_b32 v[82:83], v15 offset0:222 offset1:255
	s_add_u32 s95, s94, 0xe00
	s_min_u32 s95, s95, 0xfff
	s_lshr_b32 vcc_lo, s95, 7
	s_and_b32 vcc_hi, s95, 0x7f
	s_mul_i32 vcc_hi, vcc_hi, 0x20000
	s_lshl_b32 vcc_lo, vcc_lo, 7
	s_add_u32 s98, s66, 0x4100000
	s_addc_u32 s99, s67, 0
	s_add_u32 s98, s98, vcc_hi
	s_addc_u32 s99, s99, 0
	s_add_u32 s98, s98, vcc_lo
	s_addc_u32 s99, s99, 0
	s_waitcnt lgkmcnt(0)
	v_cvt_pk_bf16_f32 v84, v52, v53
	v_cvt_pk_bf16_f32 v85, v54, v55
	v_cvt_pk_bf16_f32 v86, v56, v57
	v_cvt_pk_bf16_f32 v87, v58, v59
	v_cvt_pk_bf16_f32 v88, v60, v61
	v_cvt_pk_bf16_f32 v89, v62, v63
	v_cvt_pk_bf16_f32 v90, v64, v65
	v_cvt_pk_bf16_f32 v91, v66, v67
	v_cvt_pk_bf16_f32 v92, v68, v69
	v_cvt_pk_bf16_f32 v93, v70, v71
	v_cvt_pk_bf16_f32 v94, v72, v73
	v_cvt_pk_bf16_f32 v95, v74, v75
	v_cvt_pk_bf16_f32 v96, v76, v77
	v_cvt_pk_bf16_f32 v97, v78, v79
	v_cvt_pk_bf16_f32 v98, v80, v81
	v_cvt_pk_bf16_f32 v99, v82, v83
	global_store_dwordx4 v16, v[84:87], s[98:99]
	global_store_dwordx4 v17, v[88:91], s[98:99]
	global_store_dwordx4 v18, v[92:95], s[98:99]
	global_store_dwordx4 v19, v[96:99], s[98:99]

.LBB0_485:
	s_andn2_saveexec_b64 s[22:23], s[22:23]
	s_branch .LBB0_487
	v_add_u32_e32 v2, 0xc000, v30
	v_lshrrev_b32_e32 v2, 1, v2
	v_and_b32_e32 v88, 0xfe0, v43
	v_and_b32_e32 v84, 0x7fc0, v2
	v_lshlrev_b32_e32 v2, 2, v88
	v_lshl_add_u64 v[80:81], v[22:23], 0, v[2:3]
	v_or_b32_e32 v2, v84, v31
	v_lshlrev_b32_e32 v2, 14, v2
	v_lshl_add_u64 v[26:27], v[80:81], 0, v[2:3]
	v_or_b32_e32 v2, v84, v32
	v_lshlrev_b32_e32 v2, 14, v2
	v_lshl_add_u64 v[56:57], v[80:81], 0, v[2:3]
	v_or_b32_e32 v2, v84, v33
	v_lshlrev_b32_e32 v2, 14, v2
	v_lshl_add_u64 v[60:61], v[80:81], 0, v[2:3]
	v_or_b32_e32 v2, v84, v34
	v_lshlrev_b32_e32 v2, 14, v2
	v_lshl_add_u64 v[64:65], v[80:81], 0, v[2:3]
	v_or_b32_e32 v2, v84, v35
	v_lshlrev_b32_e32 v2, 14, v2
	v_lshl_add_u64 v[68:69], v[80:81], 0, v[2:3]
	v_or_b32_e32 v2, v84, v36
	v_lshlrev_b32_e32 v2, 14, v2
	v_lshl_add_u64 v[72:73], v[80:81], 0, v[2:3]
	global_load_dwordx4 v[26:29], v[26:27], off
	s_nop 0
	global_load_dwordx4 v[56:59], v[56:57], off
	s_nop 0
	global_load_dwordx4 v[60:63], v[60:61], off
	s_nop 0
	global_load_dwordx4 v[64:67], v[64:65], off
	s_nop 0
	global_load_dwordx4 v[68:71], v[68:69], off
	s_nop 0
	global_load_dwordx4 v[72:75], v[72:73], off
	v_or_b32_e32 v2, v84, v37
	v_lshlrev_b32_e32 v2, 14, v2
	v_lshl_add_u64 v[76:77], v[80:81], 0, v[2:3]
	v_or_b32_e32 v2, v84, v38
	global_load_dwordx4 v[76:79], v[76:77], off
	v_lshlrev_b32_e32 v2, 14, v2
	v_lshl_add_u64 v[80:81], v[80:81], 0, v[2:3]
	global_load_dwordx4 v[80:83], v[80:81], off
	v_add_u32_e32 v89, 0x18c8, v44
	v_add_u32_e32 v90, 0x1ce0, v44
	v_add_u32_e32 v91, 0x1ce8, v44
	v_or_b32_e32 v86, v88, v31
	v_lshlrev_b32_e32 v2, 1, v84
	v_lshl_add_u64 v[84:85], v[12:13], 0, v[2:3]
	v_lshlrev_b32_e32 v2, 12, v86
	v_lshl_add_u64 v[86:87], v[84:85], 0, v[2:3]
	s_waitcnt vmcnt(7)
	ds_write2_b32 v44, v26, v27 offset1:1
	ds_write2_b32 v44, v28, v29 offset0:2 offset1:3
	s_waitcnt vmcnt(6)
	ds_write2_b32 v45, v56, v57 offset1:1
	ds_write2_b32 v46, v58, v59 offset1:1
	s_waitcnt vmcnt(5)
	ds_write2_b32 v47, v60, v61 offset1:1
	ds_write2_b32 v48, v62, v63 offset1:1
	s_waitcnt vmcnt(4)
	ds_write2_b32 v49, v64, v65 offset1:1
	ds_write2_b32 v50, v66, v67 offset1:1
	s_waitcnt vmcnt(3)
	ds_write2_b32 v51, v68, v69 offset1:1
	ds_write2_b32 v52, v70, v71 offset1:1
	s_waitcnt vmcnt(2)
	ds_write2_b32 v53, v72, v73 offset1:1
	ds_write2_b32 v54, v74, v75 offset1:1
	s_waitcnt vmcnt(1)
	ds_write2_b32 v55, v76, v77 offset1:1
	ds_write2_b32 v89, v78, v79 offset1:1
	s_waitcnt vmcnt(0)
	ds_write2_b32 v90, v80, v81 offset1:1
	ds_write2_b32 v91, v82, v83 offset1:1
	s_waitcnt lgkmcnt(0)
	ds_read2_b32 v[26:27], v39 offset0:33 offset1:41
	ds_read2_b32 v[28:29], v39 offset1:8
	ds_read2_b32 v[56:57], v39 offset0:66 offset1:74
	ds_read2_b32 v[58:59], v39 offset0:99 offset1:107
	ds_read2_b32 v[60:61], v39 offset0:132 offset1:140
	ds_read2_b32 v[62:63], v39 offset0:165 offset1:173
	ds_read2_b32 v[64:65], v39 offset0:198 offset1:206
	ds_read2_b32 v[66:67], v39 offset0:231 offset1:239
	s_waitcnt lgkmcnt(6)
	v_bfe_u32 v2, v28, 16, 1
	s_waitcnt lgkmcnt(5)
	v_bfe_u32 v69, v56, 16, 1
	s_waitcnt lgkmcnt(4)
	v_bfe_u32 v70, v58, 16, 1
	s_waitcnt lgkmcnt(3)
	v_bfe_u32 v71, v60, 16, 1
	s_waitcnt lgkmcnt(2)
	v_bfe_u32 v72, v62, 16, 1
	s_waitcnt lgkmcnt(1)
	v_bfe_u32 v73, v64, 16, 1
	v_bfe_u32 v68, v26, 16, 1
	s_waitcnt lgkmcnt(0)
	v_bfe_u32 v74, v66, 16, 1
	v_bfe_u32 v75, v29, 16, 1
	v_bfe_u32 v76, v27, 16, 1
	v_add3_u32 v2, v28, v2, s38
	v_add3_u32 v28, v56, v69, s38
	v_add3_u32 v56, v58, v70, s38
	v_add3_u32 v58, v60, v71, s38
	v_add3_u32 v60, v62, v72, s38
	v_add3_u32 v62, v64, v73, s38
	v_add3_u32 v26, v26, v68, s38
	v_add3_u32 v64, v66, v74, s38
	v_add3_u32 v29, v29, v75, s38
	v_add3_u32 v66, v27, v76, s38
	v_lshrrev_b32_e32 v2, 16, v2
	v_lshrrev_b32_e32 v27, 16, v28
	v_lshrrev_b32_e32 v28, 16, v58
	v_lshrrev_b32_e32 v58, 16, v62
	v_bfe_u32 v77, v57, 16, 1
	v_lshrrev_b32_e32 v62, 16, v29
	v_and_or_b32 v26, v26, s40, v2
	v_and_or_b32 v27, v56, s40, v27
	v_and_or_b32 v28, v60, s40, v28
	v_and_or_b32 v29, v64, s40, v58
	v_add3_u32 v57, v57, v77, s38
	global_store_dwordx4 v[86:87], v[26:29], off
	v_lshrrev_b32_e32 v2, 16, v57
	v_and_or_b32 v56, v66, s40, v62
	v_bfe_u32 v26, v59, 16, 1
	v_add3_u32 v26, v59, v26, s38
	v_and_or_b32 v57, v26, s40, v2
	v_bfe_u32 v2, v61, 16, 1
	v_add3_u32 v2, v61, v2, s38
	v_bfe_u32 v26, v63, 16, 1
	v_lshrrev_b32_e32 v2, 16, v2
	v_add3_u32 v26, v63, v26, s38
	v_and_or_b32 v58, v26, s40, v2
	v_bfe_u32 v2, v65, 16, 1
	v_add3_u32 v2, v65, v2, s38
	v_bfe_u32 v26, v67, 16, 1
	v_lshrrev_b32_e32 v2, 16, v2
	v_add3_u32 v26, v67, v26, s38
	v_and_or_b32 v59, v26, s40, v2
	v_or_b32_e32 v2, v88, v32
	v_lshlrev_b32_e32 v2, 12, v2
	ds_read2_b32 v[60:61], v39 offset0:16 offset1:24
	v_lshl_add_u64 v[26:27], v[84:85], 0, v[2:3]
	global_store_dwordx4 v[26:27], v[56:59], off
	ds_read2_b32 v[56:57], v39 offset0:49 offset1:57
	ds_read2_b32 v[58:59], v39 offset0:82 offset1:90
	ds_read2_b32 v[62:63], v39 offset0:115 offset1:123
	s_waitcnt lgkmcnt(3)
	v_bfe_u32 v2, v60, 16, 1
	v_add3_u32 v2, v60, v2, s38
	s_waitcnt lgkmcnt(2)
	v_bfe_u32 v26, v56, 16, 1
	ds_read2_b32 v[64:65], v39 offset0:148 offset1:156
	v_lshrrev_b32_e32 v2, 16, v2
	v_add3_u32 v26, v56, v26, s38
	ds_read2_b32 v[66:67], v39 offset0:181 offset1:189
	v_and_or_b32 v26, v26, s40, v2
	s_waitcnt lgkmcnt(3)
	v_bfe_u32 v2, v58, 16, 1
	v_add3_u32 v2, v58, v2, s38
	s_waitcnt lgkmcnt(2)
	v_bfe_u32 v27, v62, 16, 1
	ds_read2_b32 v[68:69], v39 offset0:214 offset1:222
	v_lshrrev_b32_e32 v2, 16, v2
	v_add3_u32 v27, v62, v27, s38
	ds_read2_b32 v[70:71], v39 offset0:247 offset1:255
	v_and_or_b32 v27, v27, s40, v2
	s_waitcnt lgkmcnt(3)
	v_bfe_u32 v2, v64, 16, 1
	v_add3_u32 v2, v64, v2, s38
	s_waitcnt lgkmcnt(2)
	v_bfe_u32 v28, v66, 16, 1
	v_lshrrev_b32_e32 v2, 16, v2
	v_add3_u32 v28, v66, v28, s38
	v_and_or_b32 v28, v28, s40, v2
	s_waitcnt lgkmcnt(1)
	v_bfe_u32 v2, v68, 16, 1
	v_add3_u32 v2, v68, v2, s38
	s_waitcnt lgkmcnt(0)
	v_bfe_u32 v29, v70, 16, 1
	v_lshrrev_b32_e32 v2, 16, v2
	v_add3_u32 v29, v70, v29, s38
	v_and_or_b32 v29, v29, s40, v2
	v_or_b32_e32 v2, v88, v33
	v_lshlrev_b32_e32 v2, 12, v2
	v_lshl_add_u64 v[72:73], v[84:85], 0, v[2:3]
	v_bfe_u32 v2, v61, 16, 1
	global_store_dwordx4 v[72:73], v[26:29], off
	v_add3_u32 v2, v61, v2, s38
	v_lshrrev_b32_e32 v2, 16, v2
	v_bfe_u32 v26, v57, 16, 1
	v_add3_u32 v26, v57, v26, s38
	v_and_or_b32 v26, v26, s40, v2
	v_bfe_u32 v2, v59, 16, 1
	v_add3_u32 v2, v59, v2, s38
	v_bfe_u32 v27, v63, 16, 1
	v_lshrrev_b32_e32 v2, 16, v2
	v_add3_u32 v27, v63, v27, s38
	v_and_or_b32 v27, v27, s40, v2
	v_bfe_u32 v2, v65, 16, 1
	v_add3_u32 v2, v65, v2, s38
	v_bfe_u32 v28, v67, 16, 1
	v_lshrrev_b32_e32 v2, 16, v2
	v_add3_u32 v28, v67, v28, s38
	v_and_or_b32 v28, v28, s40, v2
	v_bfe_u32 v2, v69, 16, 1
	v_add3_u32 v2, v69, v2, s38
	v_bfe_u32 v29, v71, 16, 1
	v_lshrrev_b32_e32 v2, 16, v2
	v_add3_u32 v29, v71, v29, s38
	v_and_or_b32 v29, v29, s40, v2
	v_or_b32_e32 v2, v88, v34
	v_lshlrev_b32_e32 v2, 12, v2
	v_lshl_add_u64 v[56:57], v[84:85], 0, v[2:3]
	global_store_dwordx4 v[56:57], v[26:29], off
	s_waitcnt lgkmcnt(0)

.LBB0_1906:
	s_waitcnt vmcnt(0)
	s_mov_b32 s2, s86
	s_barrier
	v_readlane_b32 s94, v254, 0
	v_readfirstlane_b32 s95, v0
	s_nop 3
	s_cmpk_lt_u32 s94, 0x80
	s_cbranch_scc1 .Lwf_done
	s_lshr_b32 s95, s95, 6
	s_sub_u32 s94, s94, 0x80
	s_lshl_b32 s94, s94, 3
	s_add_u32 s94, s94, s95
	v_readlane_b32 s96, v254, 2
	v_readlane_b32 s97, v254, 3
	s_nop 3
	s_sub_u32 s96, s96, 0x28
	s_subb_u32 s97, s97, 0
	s_load_dwordx2 s[100:101], s[96:97], 0x0
	s_add_u32 s94, s94, 0x600
	v_and_b32_e32 v2, 63, v0
	v_lshrrev_b32_e32 v3, 3, v2
	v_and_b32_e32 v4, 7, v2
	v_lshlrev_b32_e32 v5, 14, v3
	v_lshl_add_u32 v5, v4, 4, v5
	v_add_u32_e32 v6, 0x0, v5
	v_add_u32_e32 v7, 0x20000, v5
	v_add_u32_e32 v8, 0x40000, v5
	v_add_u32_e32 v9, 0x60000, v5
	v_add_u32_e32 v10, 0x80000, v5
	v_add_u32_e32 v11, 0xa0000, v5
	v_add_u32_e32 v12, 0xc0000, v5
	v_add_u32_e32 v13, 0xe0000, v5
	s_lshl_b32 s95, s95, 14
	v_mul_u32_u24_e32 v14, 0x84, v3
	v_lshl_add_u32 v14, v4, 4, v14
	v_add_u32_e32 v14, s95, v14
	v_mul_u32_u24_e32 v15, 0x420, v4
	v_lshl_add_u32 v15, v3, 2, v15
	v_add_u32_e32 v15, s95, v15
	v_mul_u32_u24_e32 v16, 0x5600, v3
	v_lshl_add_u32 v16, v4, 4, v16
	v_add_u32_e32 v17, 0x2b000, v16
	v_add_u32_e32 v18, 0x56000, v16
	v_add_u32_e32 v19, 0x81000, v16
	s_waitcnt lgkmcnt(0)
	s_mov_b32 s95, s94
	s_lshr_b32 vcc_lo, s95, 7
	s_and_b32 vcc_hi, s95, 0x7f
	s_lshl_b32 vcc_lo, vcc_lo, 20
	s_lshl_b32 vcc_hi, vcc_hi, 7
	s_add_u32 s96, s100, vcc_lo
	s_addc_u32 s97, s101, 0
	s_add_u32 s96, s96, vcc_hi
	s_addc_u32 s97, s97, 0
	global_load_dwordx4 v[20:23], v6, s[96:97]
	global_load_dwordx4 v[24:27], v7, s[96:97]
	global_load_dwordx4 v[28:31], v8, s[96:97]
	global_load_dwordx4 v[32:35], v9, s[96:97]
	global_load_dwordx4 v[36:39], v10, s[96:97]
	global_load_dwordx4 v[40:43], v11, s[96:97]
	global_load_dwordx4 v[44:47], v12, s[96:97]
	global_load_dwordx4 v[48:51], v13, s[96:97]
	s_add_u32 s95, s94, 0x400
	s_lshr_b32 vcc_lo, s95, 7
	s_and_b32 vcc_hi, s95, 0x7f
	s_lshl_b32 vcc_lo, vcc_lo, 20
	s_lshl_b32 vcc_hi, vcc_hi, 7
	s_add_u32 s96, s100, vcc_lo
	s_addc_u32 s97, s101, 0
	s_add_u32 s96, s96, vcc_hi
	s_addc_u32 s97, s97, 0
	global_load_dwordx4 v[100:103], v6, s[96:97]
	global_load_dwordx4 v[104:107], v7, s[96:97]
	global_load_dwordx4 v[108:111], v8, s[96:97]
	global_load_dwordx4 v[112:115], v9, s[96:97]
	global_load_dwordx4 v[116:119], v10, s[96:97]
	global_load_dwordx4 v[120:123], v11, s[96:97]
	global_load_dwordx4 v[124:127], v12, s[96:97]
	global_load_dwordx4 v[128:131], v13, s[96:97]
	s_waitcnt vmcnt(15)
	ds_write_b32 v14, v20 offset:0
	ds_write_b32 v14, v21 offset:4
	ds_write_b32 v14, v22 offset:8
	ds_write_b32 v14, v23 offset:12
	s_waitcnt vmcnt(14)
	ds_write_b32 v14, v24 offset:1056
	ds_write_b32 v14, v25 offset:1060
	ds_write_b32 v14, v26 offset:1064
	ds_write_b32 v14, v27 offset:1068
	s_waitcnt vmcnt(13)
	ds_write_b32 v14, v28 offset:2112
	ds_write_b32 v14, v29 offset:2116
	ds_write_b32 v14, v30 offset:2120
	ds_write_b32 v14, v31 offset:2124
	s_waitcnt vmcnt(12)
	ds_write_b32 v14, v32 offset:3168
	ds_write_b32 v14, v33 offset:3172
	ds_write_b32 v14, v34 offset:3176
	ds_write_b32 v14, v35 offset:3180
	s_waitcnt vmcnt(11)
	ds_write_b32 v14, v36 offset:4224
	ds_write_b32 v14, v37 offset:4228
	ds_write_b32 v14, v38 offset:4232
	ds_write_b32 v14, v39 offset:4236
	s_waitcnt vmcnt(10)
	ds_write_b32 v14, v40 offset:5280
	ds_write_b32 v14, v41 offset:5284
	ds_write_b32 v14, v42 offset:5288
	ds_write_b32 v14, v43 offset:5292
	s_waitcnt vmcnt(9)
	ds_write_b32 v14, v44 offset:6336
	ds_write_b32 v14, v45 offset:6340
	ds_write_b32 v14, v46 offset:6344
	ds_write_b32 v14, v47 offset:6348
	s_waitcnt vmcnt(8)
	ds_write_b32 v14, v48 offset:7392
	ds_write_b32 v14, v49 offset:7396
	ds_write_b32 v14, v50 offset:7400
	ds_write_b32 v14, v51 offset:7404
	s_add_u32 s95, s94, 0x800
	s_lshr_b32 vcc_lo, s95, 7
	s_and_b32 vcc_hi, s95, 0x7f
	s_lshl_b32 vcc_lo, vcc_lo, 20
	s_lshl_b32 vcc_hi, vcc_hi, 7
	s_add_u32 s96, s100, vcc_lo
	s_addc_u32 s97, s101, 0
	s_add_u32 s96, s96, vcc_hi
	s_addc_u32 s97, s97, 0
	global_load_dwordx4 v[20:23], v6, s[96:97]
	global_load_dwordx4 v[24:27], v7, s[96:97]
	global_load_dwordx4 v[28:31], v8, s[96:97]
	global_load_dwordx4 v[32:35], v9, s[96:97]
	global_load_dwordx4 v[36:39], v10, s[96:97]
	global_load_dwordx4 v[40:43], v11, s[96:97]
	global_load_dwordx4 v[44:47], v12, s[96:97]
	global_load_dwordx4 v[48:51], v13, s[96:97]
	ds_read2_b32 v[52:53], v15 offset0:0 offset1:33
	ds_read2_b32 v[54:55], v15 offset0:66 offset1:99
	ds_read2_b32 v[56:57], v15 offset0:132 offset1:165
	ds_read2_b32 v[58:59], v15 offset0:198 offset1:231
	ds_read2_b32 v[60:61], v15 offset0:8 offset1:41
	ds_read2_b32 v[62:63], v15 offset0:74 offset1:107
	ds_read2_b32 v[64:65], v15 offset0:140 offset1:173
	ds_read2_b32 v[66:67], v15 offset0:206 offset1:239
	ds_read2_b32 v[68:69], v15 offset0:16 offset1:49
	ds_read2_b32 v[70:71], v15 offset0:82 offset1:115
	ds_read2_b32 v[72:73], v15 offset0:148 offset1:181
	ds_read2_b32 v[74:75], v15 offset0:214 offset1:247
	ds_read2_b32 v[76:77], v15 offset0:24 offset1:57
	ds_read2_b32 v[78:79], v15 offset0:90 offset1:123
	ds_read2_b32 v[80:81], v15 offset0:156 offset1:189
	ds_read2_b32 v[82:83], v15 offset0:222 offset1:255
	s_mov_b32 s95, s94
	s_lshr_b32 vcc_lo, s95, 7
	s_and_b32 vcc_hi, s95, 0x7f
	s_mul_i32 vcc_hi, vcc_hi, 0xac000
	s_lshl_b32 vcc_lo, vcc_lo, 7
	s_add_u32 s98, s66, 0x12d00000
	s_addc_u32 s99, s67, 0
	s_add_u32 s98, s98, vcc_hi
	s_addc_u32 s99, s99, 0
	s_add_u32 s98, s98, vcc_lo
	s_addc_u32 s99, s99, 0
	s_waitcnt lgkmcnt(0)
	v_cvt_pk_bf16_f32 v84, v52, v53
	v_cvt_pk_bf16_f32 v85, v54, v55
	v_cvt_pk_bf16_f32 v86, v56, v57
	v_cvt_pk_bf16_f32 v87, v58, v59
	v_cvt_pk_bf16_f32 v88, v60, v61
	v_cvt_pk_bf16_f32 v89, v62, v63
	v_cvt_pk_bf16_f32 v90, v64, v65
	v_cvt_pk_bf16_f32 v91, v66, v67
	v_cvt_pk_bf16_f32 v92, v68, v69
	v_cvt_pk_bf16_f32 v93, v70, v71
	v_cvt_pk_bf16_f32 v94, v72, v73
	v_cvt_pk_bf16_f32 v95, v74, v75
	v_cvt_pk_bf16_f32 v96, v76, v77
	v_cvt_pk_bf16_f32 v97, v78, v79
	v_cvt_pk_bf16_f32 v98, v80, v81
	v_cvt_pk_bf16_f32 v99, v82, v83
	global_store_dwordx4 v16, v[84:87], s[98:99]
	global_store_dwordx4 v17, v[88:91], s[98:99]
	global_store_dwordx4 v18, v[92:95], s[98:99]
	global_store_dwordx4 v19, v[96:99], s[98:99]
	s_waitcnt vmcnt(19)
	ds_write_b32 v14, v100 offset:0
	ds_write_b32 v14, v101 offset:4
	ds_write_b32 v14, v102 offset:8
	ds_write_b32 v14, v103 offset:12
	s_waitcnt vmcnt(18)
	ds_write_b32 v14, v104 offset:1056
	ds_write_b32 v14, v105 offset:1060
	ds_write_b32 v14, v106 offset:1064
	ds_write_b32 v14, v107 offset:1068
	s_waitcnt vmcnt(17)
	ds_write_b32 v14, v108 offset:2112
	ds_write_b32 v14, v109 offset:2116
	ds_write_b32 v14, v110 offset:2120
	ds_write_b32 v14, v111 offset:2124
	s_waitcnt vmcnt(16)
	ds_write_b32 v14, v112 offset:3168
	ds_write_b32 v14, v113 offset:3172
	ds_write_b32 v14, v114 offset:3176
	ds_write_b32 v14, v115 offset:3180
	s_waitcnt vmcnt(15)
	ds_write_b32 v14, v116 offset:4224
	ds_write_b32 v14, v117 offset:4228
	ds_write_b32 v14, v118 offset:4232
	ds_write_b32 v14, v119 offset:4236
	s_waitcnt vmcnt(14)
	ds_write_b32 v14, v120 offset:5280
	ds_write_b32 v14, v121 offset:5284
	ds_write_b32 v14, v122 offset:5288
	ds_write_b32 v14, v123 offset:5292
	s_waitcnt vmcnt(13)
	ds_write_b32 v14, v124 offset:6336
	ds_write_b32 v14, v125 offset:6340
	ds_write_b32 v14, v126 offset:6344
	ds_write_b32 v14, v127 offset:6348
	s_waitcnt vmcnt(12)
	ds_write_b32 v14, v128 offset:7392
	ds_write_b32 v14, v129 offset:7396
	ds_write_b32 v14, v130 offset:7400
	ds_write_b32 v14, v131 offset:7404
	s_add_u32 s95, s94, 0xc00
	s_lshr_b32 vcc_lo, s95, 7
	s_and_b32 vcc_hi, s95, 0x7f
	s_lshl_b32 vcc_lo, vcc_lo, 20
	s_lshl_b32 vcc_hi, vcc_hi, 7
	s_add_u32 s96, s100, vcc_lo
	s_addc_u32 s97, s101, 0
	s_add_u32 s96, s96, vcc_hi
	s_addc_u32 s97, s97, 0
	global_load_dwordx4 v[100:103], v6, s[96:97]
	global_load_dwordx4 v[104:107], v7, s[96:97]
	global_load_dwordx4 v[108:111], v8, s[96:97]
	global_load_dwordx4 v[112:115], v9, s[96:97]
	global_load_dwordx4 v[116:119], v10, s[96:97]
	global_load_dwordx4 v[120:123], v11, s[96:97]
	global_load_dwordx4 v[124:127], v12, s[96:97]
	global_load_dwordx4 v[128:131], v13, s[96:97]
	ds_read2_b32 v[52:53], v15 offset0:0 offset1:33
	ds_read2_b32 v[54:55], v15 offset0:66 offset1:99
	ds_read2_b32 v[56:57], v15 offset0:132 offset1:165
	ds_read2_b32 v[58:59], v15 offset0:198 offset1:231
	ds_read2_b32 v[60:61], v15 offset0:8 offset1:41
	ds_read2_b32 v[62:63], v15 offset0:74 offset1:107
	ds_read2_b32 v[64:65], v15 offset0:140 offset1:173
	ds_read2_b32 v[66:67], v15 offset0:206 offset1:239
	ds_read2_b32 v[68:69], v15 offset0:16 offset1:49
	ds_read2_b32 v[70:71], v15 offset0:82 offset1:115
	ds_read2_b32 v[72:73], v15 offset0:148 offset1:181
	ds_read2_b32 v[74:75], v15 offset0:214 offset1:247
	ds_read2_b32 v[76:77], v15 offset0:24 offset1:57
	ds_read2_b32 v[78:79], v15 offset0:90 offset1:123
	ds_read2_b32 v[80:81], v15 offset0:156 offset1:189
	ds_read2_b32 v[82:83], v15 offset0:222 offset1:255
	s_add_u32 s95, s94, 0x400
	s_lshr_b32 vcc_lo, s95, 7
	s_and_b32 vcc_hi, s95, 0x7f
	s_mul_i32 vcc_hi, vcc_hi, 0xac000
	s_lshl_b32 vcc_lo, vcc_lo, 7
	s_add_u32 s98, s66, 0x12d00000
	s_addc_u32 s99, s67, 0
	s_add_u32 s98, s98, vcc_hi
	s_addc_u32 s99, s99, 0
	s_add_u32 s98, s98, vcc_lo
	s_addc_u32 s99, s99, 0
	s_waitcnt lgkmcnt(0)
	v_cvt_pk_bf16_f32 v84, v52, v53
	v_cvt_pk_bf16_f32 v85, v54, v55
	v_cvt_pk_bf16_f32 v86, v56, v57
	v_cvt_pk_bf16_f32 v87, v58, v59
	v_cvt_pk_bf16_f32 v88, v60, v61
	v_cvt_pk_bf16_f32 v89, v62, v63
	v_cvt_pk_bf16_f32 v90, v64, v65
	v_cvt_pk_bf16_f32 v91, v66, v67
	v_cvt_pk_bf16_f32 v92, v68, v69
	v_cvt_pk_bf16_f32 v93, v70, v71
	v_cvt_pk_bf16_f32 v94, v72, v73
	v_cvt_pk_bf16_f32 v95, v74, v75
	v_cvt_pk_bf16_f32 v96, v76, v77
	v_cvt_pk_bf16_f32 v97, v78, v79
	v_cvt_pk_bf16_f32 v98, v80, v81
	v_cvt_pk_bf16_f32 v99, v82, v83
	global_store_dwordx4 v16, v[84:87], s[98:99]
	global_store_dwordx4 v17, v[88:91], s[98:99]
	global_store_dwordx4 v18, v[92:95], s[98:99]
	global_store_dwordx4 v19, v[96:99], s[98:99]
	s_waitcnt vmcnt(23)
	ds_write_b32 v14, v20 offset:0
	ds_write_b32 v14, v21 offset:4
	ds_write_b32 v14, v22 offset:8
	ds_write_b32 v14, v23 offset:12
	s_waitcnt vmcnt(22)
	ds_write_b32 v14, v24 offset:1056
	ds_write_b32 v14, v25 offset:1060
	ds_write_b32 v14, v26 offset:1064
	ds_write_b32 v14, v27 offset:1068
	s_waitcnt vmcnt(21)
	ds_write_b32 v14, v28 offset:2112
	ds_write_b32 v14, v29 offset:2116
	ds_write_b32 v14, v30 offset:2120
	ds_write_b32 v14, v31 offset:2124
	s_waitcnt vmcnt(20)
	ds_write_b32 v14, v32 offset:3168
	ds_write_b32 v14, v33 offset:3172
	ds_write_b32 v14, v34 offset:3176
	ds_write_b32 v14, v35 offset:3180
	s_waitcnt vmcnt(19)
	ds_write_b32 v14, v36 offset:4224
	ds_write_b32 v14, v37 offset:4228
	ds_write_b32 v14, v38 offset:4232
	ds_write_b32 v14, v39 offset:4236
	s_waitcnt vmcnt(18)
	ds_write_b32 v14, v40 offset:5280
	ds_write_b32 v14, v41 offset:5284
	ds_write_b32 v14, v42 offset:5288
	ds_write_b32 v14, v43 offset:5292
	s_waitcnt vmcnt(17)
	ds_write_b32 v14, v44 offset:6336
	ds_write_b32 v14, v45 offset:6340
	ds_write_b32 v14, v46 offset:6344
	ds_write_b32 v14, v47 offset:6348
	s_waitcnt vmcnt(16)
	ds_write_b32 v14, v48 offset:7392
	ds_write_b32 v14, v49 offset:7396
	ds_write_b32 v14, v50 offset:7400
	ds_write_b32 v14, v51 offset:7404
	s_add_u32 s95, s94, 0x1000
	s_lshr_b32 vcc_lo, s95, 7
	s_and_b32 vcc_hi, s95, 0x7f
	s_lshl_b32 vcc_lo, vcc_lo, 20
	s_lshl_b32 vcc_hi, vcc_hi, 7
	s_add_u32 s96, s100, vcc_lo
	s_addc_u32 s97, s101, 0
	s_add_u32 s96, s96, vcc_hi
	s_addc_u32 s97, s97, 0
	global_load_dwordx4 v[20:23], v6, s[96:97]
	global_load_dwordx4 v[24:27], v7, s[96:97]
	global_load_dwordx4 v[28:31], v8, s[96:97]
	global_load_dwordx4 v[32:35], v9, s[96:97]
	global_load_dwordx4 v[36:39], v10, s[96:97]
	global_load_dwordx4 v[40:43], v11, s[96:97]
	global_load_dwordx4 v[44:47], v12, s[96:97]
	global_load_dwordx4 v[48:51], v13, s[96:97]
	ds_read2_b32 v[52:53], v15 offset0:0 offset1:33
	ds_read2_b32 v[54:55], v15 offset0:66 offset1:99
	ds_read2_b32 v[56:57], v15 offset0:132 offset1:165
	ds_read2_b32 v[58:59], v15 offset0:198 offset1:231
	ds_read2_b32 v[60:61], v15 offset0:8 offset1:41
	ds_read2_b32 v[62:63], v15 offset0:74 offset1:107
	ds_read2_b32 v[64:65], v15 offset0:140 offset1:173
	ds_read2_b32 v[66:67], v15 offset0:206 offset1:239
	ds_read2_b32 v[68:69], v15 offset0:16 offset1:49
	ds_read2_b32 v[70:71], v15 offset0:82 offset1:115
	ds_read2_b32 v[72:73], v15 offset0:148 offset1:181
	ds_read2_b32 v[74:75], v15 offset0:214 offset1:247
	ds_read2_b32 v[76:77], v15 offset0:24 offset1:57
	ds_read2_b32 v[78:79], v15 offset0:90 offset1:123
	ds_read2_b32 v[80:81], v15 offset0:156 offset1:189
	ds_read2_b32 v[82:83], v15 offset0:222 offset1:255
	s_add_u32 s95, s94, 0x800
	s_lshr_b32 vcc_lo, s95, 7
	s_and_b32 vcc_hi, s95, 0x7f
	s_mul_i32 vcc_hi, vcc_hi, 0xac000
	s_lshl_b32 vcc_lo, vcc_lo, 7
	s_add_u32 s98, s66, 0x12d00000
	s_addc_u32 s99, s67, 0
	s_add_u32 s98, s98, vcc_hi
	s_addc_u32 s99, s99, 0
	s_add_u32 s98, s98, vcc_lo
	s_addc_u32 s99, s99, 0
	s_waitcnt lgkmcnt(0)
	v_cvt_pk_bf16_f32 v84, v52, v53
	v_cvt_pk_bf16_f32 v85, v54, v55
	v_cvt_pk_bf16_f32 v86, v56, v57
	v_cvt_pk_bf16_f32 v87, v58, v59
	v_cvt_pk_bf16_f32 v88, v60, v61
	v_cvt_pk_bf16_f32 v89, v62, v63
	v_cvt_pk_bf16_f32 v90, v64, v65
	v_cvt_pk_bf16_f32 v91, v66, v67
	v_cvt_pk_bf16_f32 v92, v68, v69
	v_cvt_pk_bf16_f32 v93, v70, v71
	v_cvt_pk_bf16_f32 v94, v72, v73
	v_cvt_pk_bf16_f32 v95, v74, v75
	v_cvt_pk_bf16_f32 v96, v76, v77
	v_cvt_pk_bf16_f32 v97, v78, v79
	v_cvt_pk_bf16_f32 v98, v80, v81
	v_cvt_pk_bf16_f32 v99, v82, v83
	global_store_dwordx4 v16, v[84:87], s[98:99]
	global_store_dwordx4 v17, v[88:91], s[98:99]
	global_store_dwordx4 v18, v[92:95], s[98:99]
	global_store_dwordx4 v19, v[96:99], s[98:99]
	s_waitcnt vmcnt(23)
	ds_write_b32 v14, v100 offset:0
	ds_write_b32 v14, v101 offset:4
	ds_write_b32 v14, v102 offset:8
	ds_write_b32 v14, v103 offset:12
	s_waitcnt vmcnt(22)
	ds_write_b32 v14, v104 offset:1056
	ds_write_b32 v14, v105 offset:1060
	ds_write_b32 v14, v106 offset:1064
	ds_write_b32 v14, v107 offset:1068
	s_waitcnt vmcnt(21)
	ds_write_b32 v14, v108 offset:2112
	ds_write_b32 v14, v109 offset:2116
	ds_write_b32 v14, v110 offset:2120
	ds_write_b32 v14, v111 offset:2124
	s_waitcnt vmcnt(20)
	ds_write_b32 v14, v112 offset:3168
	ds_write_b32 v14, v113 offset:3172
	ds_write_b32 v14, v114 offset:3176
	ds_write_b32 v14, v115 offset:3180
	s_waitcnt vmcnt(19)
	ds_write_b32 v14, v116 offset:4224
	ds_write_b32 v14, v117 offset:4228
	ds_write_b32 v14, v118 offset:4232
	ds_write_b32 v14, v119 offset:4236
	s_waitcnt vmcnt(18)
	ds_write_b32 v14, v120 offset:5280
	ds_write_b32 v14, v121 offset:5284
	ds_write_b32 v14, v122 offset:5288
	ds_write_b32 v14, v123 offset:5292
	s_waitcnt vmcnt(17)
	ds_write_b32 v14, v124 offset:6336
	ds_write_b32 v14, v125 offset:6340
	ds_write_b32 v14, v126 offset:6344
	ds_write_b32 v14, v127 offset:6348
	s_waitcnt vmcnt(16)
	ds_write_b32 v14, v128 offset:7392
	ds_write_b32 v14, v129 offset:7396
	ds_write_b32 v14, v130 offset:7400
	ds_write_b32 v14, v131 offset:7404
	s_add_u32 s95, s94, 0x1400
	s_lshr_b32 vcc_lo, s95, 7
	s_and_b32 vcc_hi, s95, 0x7f
	s_lshl_b32 vcc_lo, vcc_lo, 20
	s_lshl_b32 vcc_hi, vcc_hi, 7
	s_add_u32 s96, s100, vcc_lo
	s_addc_u32 s97, s101, 0
	s_add_u32 s96, s96, vcc_hi
	s_addc_u32 s97, s97, 0
	global_load_dwordx4 v[100:103], v6, s[96:97]
	global_load_dwordx4 v[104:107], v7, s[96:97]
	global_load_dwordx4 v[108:111], v8, s[96:97]
	global_load_dwordx4 v[112:115], v9, s[96:97]
	global_load_dwordx4 v[116:119], v10, s[96:97]
	global_load_dwordx4 v[120:123], v11, s[96:97]
	global_load_dwordx4 v[124:127], v12, s[96:97]
	global_load_dwordx4 v[128:131], v13, s[96:97]
	ds_read2_b32 v[52:53], v15 offset0:0 offset1:33
	ds_read2_b32 v[54:55], v15 offset0:66 offset1:99
	ds_read2_b32 v[56:57], v15 offset0:132 offset1:165
	ds_read2_b32 v[58:59], v15 offset0:198 offset1:231
	ds_read2_b32 v[60:61], v15 offset0:8 offset1:41
	ds_read2_b32 v[62:63], v15 offset0:74 offset1:107
	ds_read2_b32 v[64:65], v15 offset0:140 offset1:173
	ds_read2_b32 v[66:67], v15 offset0:206 offset1:239
	ds_read2_b32 v[68:69], v15 offset0:16 offset1:49
	ds_read2_b32 v[70:71], v15 offset0:82 offset1:115
	ds_read2_b32 v[72:73], v15 offset0:148 offset1:181
	ds_read2_b32 v[74:75], v15 offset0:214 offset1:247
	ds_read2_b32 v[76:77], v15 offset0:24 offset1:57
	ds_read2_b32 v[78:79], v15 offset0:90 offset1:123
	ds_read2_b32 v[80:81], v15 offset0:156 offset1:189
	ds_read2_b32 v[82:83], v15 offset0:222 offset1:255
	s_add_u32 s95, s94, 0xc00
	s_lshr_b32 vcc_lo, s95, 7
	s_and_b32 vcc_hi, s95, 0x7f
	s_mul_i32 vcc_hi, vcc_hi, 0xac000
	s_lshl_b32 vcc_lo, vcc_lo, 7
	s_add_u32 s98, s66, 0x12d00000
	s_addc_u32 s99, s67, 0
	s_add_u32 s98, s98, vcc_hi
	s_addc_u32 s99, s99, 0
	s_add_u32 s98, s98, vcc_lo
	s_addc_u32 s99, s99, 0
	s_waitcnt lgkmcnt(0)
	v_cvt_pk_bf16_f32 v84, v52, v53
	v_cvt_pk_bf16_f32 v85, v54, v55
	v_cvt_pk_bf16_f32 v86, v56, v57
	v_cvt_pk_bf16_f32 v87, v58, v59
	v_cvt_pk_bf16_f32 v88, v60, v61
	v_cvt_pk_bf16_f32 v89, v62, v63
	v_cvt_pk_bf16_f32 v90, v64, v65
	v_cvt_pk_bf16_f32 v91, v66, v67
	v_cvt_pk_bf16_f32 v92, v68, v69
	v_cvt_pk_bf16_f32 v93, v70, v71
	v_cvt_pk_bf16_f32 v94, v72, v73
	v_cvt_pk_bf16_f32 v95, v74, v75
	v_cvt_pk_bf16_f32 v96, v76, v77
	v_cvt_pk_bf16_f32 v97, v78, v79
	v_cvt_pk_bf16_f32 v98, v80, v81
	v_cvt_pk_bf16_f32 v99, v82, v83
	global_store_dwordx4 v16, v[84:87], s[98:99]
	global_store_dwordx4 v17, v[88:91], s[98:99]
	global_store_dwordx4 v18, v[92:95], s[98:99]
	global_store_dwordx4 v19, v[96:99], s[98:99]
	s_waitcnt vmcnt(23)
	ds_write_b32 v14, v20 offset:0
	ds_write_b32 v14, v21 offset:4
	ds_write_b32 v14, v22 offset:8
	ds_write_b32 v14, v23 offset:12
	s_waitcnt vmcnt(22)
	ds_write_b32 v14, v24 offset:1056
	ds_write_b32 v14, v25 offset:1060
	ds_write_b32 v14, v26 offset:1064
	ds_write_b32 v14, v27 offset:1068
	s_waitcnt vmcnt(21)
	ds_write_b32 v14, v28 offset:2112
	ds_write_b32 v14, v29 offset:2116
	ds_write_b32 v14, v30 offset:2120
	ds_write_b32 v14, v31 offset:2124
	s_waitcnt vmcnt(20)
	ds_write_b32 v14, v32 offset:3168
	ds_write_b32 v14, v33 offset:3172
	ds_write_b32 v14, v34 offset:3176
	ds_write_b32 v14, v35 offset:3180
	s_waitcnt vmcnt(19)
	ds_write_b32 v14, v36 offset:4224
	ds_write_b32 v14, v37 offset:4228
	ds_write_b32 v14, v38 offset:4232
	ds_write_b32 v14, v39 offset:4236
	s_waitcnt vmcnt(18)
	ds_write_b32 v14, v40 offset:5280
	ds_write_b32 v14, v41 offset:5284
	ds_write_b32 v14, v42 offset:5288
	ds_write_b32 v14, v43 offset:5292
	s_waitcnt vmcnt(17)
	ds_write_b32 v14, v44 offset:6336
	ds_write_b32 v14, v45 offset:6340
	ds_write_b32 v14, v46 offset:6344
	ds_write_b32 v14, v47 offset:6348
	s_waitcnt vmcnt(16)
	ds_write_b32 v14, v48 offset:7392
	ds_write_b32 v14, v49 offset:7396
	ds_write_b32 v14, v50 offset:7400
	ds_write_b32 v14, v51 offset:7404
	s_add_u32 s95, s94, 0x1800
	s_lshr_b32 vcc_lo, s95, 7
	s_and_b32 vcc_hi, s95, 0x7f
	s_lshl_b32 vcc_lo, vcc_lo, 20
	s_lshl_b32 vcc_hi, vcc_hi, 7
	s_add_u32 s96, s100, vcc_lo
	s_addc_u32 s97, s101, 0
	s_add_u32 s96, s96, vcc_hi
	s_addc_u32 s97, s97, 0
	global_load_dwordx4 v[20:23], v6, s[96:97]
	global_load_dwordx4 v[24:27], v7, s[96:97]
	global_load_dwordx4 v[28:31], v8, s[96:97]
	global_load_dwordx4 v[32:35], v9, s[96:97]
	global_load_dwordx4 v[36:39], v10, s[96:97]
	global_load_dwordx4 v[40:43], v11, s[96:97]
	global_load_dwordx4 v[44:47], v12, s[96:97]
	global_load_dwordx4 v[48:51], v13, s[96:97]
	ds_read2_b32 v[52:53], v15 offset0:0 offset1:33
	ds_read2_b32 v[54:55], v15 offset0:66 offset1:99
	ds_read2_b32 v[56:57], v15 offset0:132 offset1:165
	ds_read2_b32 v[58:59], v15 offset0:198 offset1:231
	ds_read2_b32 v[60:61], v15 offset0:8 offset1:41
	ds_read2_b32 v[62:63], v15 offset0:74 offset1:107
	ds_read2_b32 v[64:65], v15 offset0:140 offset1:173
	ds_read2_b32 v[66:67], v15 offset0:206 offset1:239
	ds_read2_b32 v[68:69], v15 offset0:16 offset1:49
	ds_read2_b32 v[70:71], v15 offset0:82 offset1:115
	ds_read2_b32 v[72:73], v15 offset0:148 offset1:181
	ds_read2_b32 v[74:75], v15 offset0:214 offset1:247
	ds_read2_b32 v[76:77], v15 offset0:24 offset1:57
	ds_read2_b32 v[78:79], v15 offset0:90 offset1:123
	ds_read2_b32 v[80:81], v15 offset0:156 offset1:189
	ds_read2_b32 v[82:83], v15 offset0:222 offset1:255
	s_add_u32 s95, s94, 0x1000
	s_lshr_b32 vcc_lo, s95, 7
	s_and_b32 vcc_hi, s95, 0x7f
	s_mul_i32 vcc_hi, vcc_hi, 0xac000
	s_lshl_b32 vcc_lo, vcc_lo, 7
	s_add_u32 s98, s66, 0x12d00000
	s_addc_u32 s99, s67, 0
	s_add_u32 s98, s98, vcc_hi
	s_addc_u32 s99, s99, 0
	s_add_u32 s98, s98, vcc_lo
	s_addc_u32 s99, s99, 0
	s_waitcnt lgkmcnt(0)
	v_cvt_pk_bf16_f32 v84, v52, v53
	v_cvt_pk_bf16_f32 v85, v54, v55
	v_cvt_pk_bf16_f32 v86, v56, v57
	v_cvt_pk_bf16_f32 v87, v58, v59
	v_cvt_pk_bf16_f32 v88, v60, v61
	v_cvt_pk_bf16_f32 v89, v62, v63
	v_cvt_pk_bf16_f32 v90, v64, v65
	v_cvt_pk_bf16_f32 v91, v66, v67
	v_cvt_pk_bf16_f32 v92, v68, v69
	v_cvt_pk_bf16_f32 v93, v70, v71
	v_cvt_pk_bf16_f32 v94, v72, v73
	v_cvt_pk_bf16_f32 v95, v74, v75
	v_cvt_pk_bf16_f32 v96, v76, v77
	v_cvt_pk_bf16_f32 v97, v78, v79
	v_cvt_pk_bf16_f32 v98, v80, v81
	v_cvt_pk_bf16_f32 v99, v82, v83
	global_store_dwordx4 v16, v[84:87], s[98:99]
	global_store_dwordx4 v17, v[88:91], s[98:99]
	global_store_dwordx4 v18, v[92:95], s[98:99]
	global_store_dwordx4 v19, v[96:99], s[98:99]
	s_waitcnt vmcnt(23)
	ds_write_b32 v14, v100 offset:0
	ds_write_b32 v14, v101 offset:4
	ds_write_b32 v14, v102 offset:8
	ds_write_b32 v14, v103 offset:12
	s_waitcnt vmcnt(22)
	ds_write_b32 v14, v104 offset:1056
	ds_write_b32 v14, v105 offset:1060
	ds_write_b32 v14, v106 offset:1064
	ds_write_b32 v14, v107 offset:1068
	s_waitcnt vmcnt(21)
	ds_write_b32 v14, v108 offset:2112
	ds_write_b32 v14, v109 offset:2116
	ds_write_b32 v14, v110 offset:2120
	ds_write_b32 v14, v111 offset:2124
	s_waitcnt vmcnt(20)
	ds_write_b32 v14, v112 offset:3168
	ds_write_b32 v14, v113 offset:3172
	ds_write_b32 v14, v114 offset:3176
	ds_write_b32 v14, v115 offset:3180
	s_waitcnt vmcnt(19)
	ds_write_b32 v14, v116 offset:4224
	ds_write_b32 v14, v117 offset:4228
	ds_write_b32 v14, v118 offset:4232
	ds_write_b32 v14, v119 offset:4236
	s_waitcnt vmcnt(18)
	ds_write_b32 v14, v120 offset:5280
	ds_write_b32 v14, v121 offset:5284
	ds_write_b32 v14, v122 offset:5288
	ds_write_b32 v14, v123 offset:5292
	s_waitcnt vmcnt(17)
	ds_write_b32 v14, v124 offset:6336
	ds_write_b32 v14, v125 offset:6340
	ds_write_b32 v14, v126 offset:6344
	ds_write_b32 v14, v127 offset:6348
	s_waitcnt vmcnt(16)
	ds_write_b32 v14, v128 offset:7392
	ds_write_b32 v14, v129 offset:7396
	ds_write_b32 v14, v130 offset:7400
	ds_write_b32 v14, v131 offset:7404
	s_add_u32 s95, s94, 0x1c00
	s_lshr_b32 vcc_lo, s95, 7
	s_and_b32 vcc_hi, s95, 0x7f
	s_lshl_b32 vcc_lo, vcc_lo, 20
	s_lshl_b32 vcc_hi, vcc_hi, 7
	s_add_u32 s96, s100, vcc_lo
	s_addc_u32 s97, s101, 0
	s_add_u32 s96, s96, vcc_hi
	s_addc_u32 s97, s97, 0
	global_load_dwordx4 v[100:103], v6, s[96:97]
	global_load_dwordx4 v[104:107], v7, s[96:97]
	global_load_dwordx4 v[108:111], v8, s[96:97]
	global_load_dwordx4 v[112:115], v9, s[96:97]
	global_load_dwordx4 v[116:119], v10, s[96:97]
	global_load_dwordx4 v[120:123], v11, s[96:97]
	global_load_dwordx4 v[124:127], v12, s[96:97]
	global_load_dwordx4 v[128:131], v13, s[96:97]
	ds_read2_b32 v[52:53], v15 offset0:0 offset1:33
	ds_read2_b32 v[54:55], v15 offset0:66 offset1:99
	ds_read2_b32 v[56:57], v15 offset0:132 offset1:165
	ds_read2_b32 v[58:59], v15 offset0:198 offset1:231
	ds_read2_b32 v[60:61], v15 offset0:8 offset1:41
	ds_read2_b32 v[62:63], v15 offset0:74 offset1:107
	ds_read2_b32 v[64:65], v15 offset0:140 offset1:173
	ds_read2_b32 v[66:67], v15 offset0:206 offset1:239
	ds_read2_b32 v[68:69], v15 offset0:16 offset1:49
	ds_read2_b32 v[70:71], v15 offset0:82 offset1:115
	ds_read2_b32 v[72:73], v15 offset0:148 offset1:181
	ds_read2_b32 v[74:75], v15 offset0:214 offset1:247
	ds_read2_b32 v[76:77], v15 offset0:24 offset1:57
	ds_read2_b32 v[78:79], v15 offset0:90 offset1:123
	ds_read2_b32 v[80:81], v15 offset0:156 offset1:189
	ds_read2_b32 v[82:83], v15 offset0:222 offset1:255
	s_add_u32 s95, s94, 0x1400
	s_lshr_b32 vcc_lo, s95, 7
	s_and_b32 vcc_hi, s95, 0x7f
	s_mul_i32 vcc_hi, vcc_hi, 0xac000
	s_lshl_b32 vcc_lo, vcc_lo, 7
	s_add_u32 s98, s66, 0x12d00000
	s_addc_u32 s99, s67, 0
	s_add_u32 s98, s98, vcc_hi
	s_addc_u32 s99, s99, 0
	s_add_u32 s98, s98, vcc_lo
	s_addc_u32 s99, s99, 0
	s_waitcnt lgkmcnt(0)
	v_cvt_pk_bf16_f32 v84, v52, v53
	v_cvt_pk_bf16_f32 v85, v54, v55
	v_cvt_pk_bf16_f32 v86, v56, v57
	v_cvt_pk_bf16_f32 v87, v58, v59
	v_cvt_pk_bf16_f32 v88, v60, v61
	v_cvt_pk_bf16_f32 v89, v62, v63
	v_cvt_pk_bf16_f32 v90, v64, v65
	v_cvt_pk_bf16_f32 v91, v66, v67
	v_cvt_pk_bf16_f32 v92, v68, v69
	v_cvt_pk_bf16_f32 v93, v70, v71
	v_cvt_pk_bf16_f32 v94, v72, v73
	v_cvt_pk_bf16_f32 v95, v74, v75
	v_cvt_pk_bf16_f32 v96, v76, v77
	v_cvt_pk_bf16_f32 v97, v78, v79
	v_cvt_pk_bf16_f32 v98, v80, v81
	v_cvt_pk_bf16_f32 v99, v82, v83
	global_store_dwordx4 v16, v[84:87], s[98:99]
	global_store_dwordx4 v17, v[88:91], s[98:99]
	global_store_dwordx4 v18, v[92:95], s[98:99]
	global_store_dwordx4 v19, v[96:99], s[98:99]
	s_waitcnt vmcnt(23)
	ds_write_b32 v14, v20 offset:0
	ds_write_b32 v14, v21 offset:4
	ds_write_b32 v14, v22 offset:8
	ds_write_b32 v14, v23 offset:12
	s_waitcnt vmcnt(22)
	ds_write_b32 v14, v24 offset:1056
	ds_write_b32 v14, v25 offset:1060
	ds_write_b32 v14, v26 offset:1064
	ds_write_b32 v14, v27 offset:1068
	s_waitcnt vmcnt(21)
	ds_write_b32 v14, v28 offset:2112
	ds_write_b32 v14, v29 offset:2116
	ds_write_b32 v14, v30 offset:2120
	ds_write_b32 v14, v31 offset:2124
	s_waitcnt vmcnt(20)
	ds_write_b32 v14, v32 offset:3168
	ds_write_b32 v14, v33 offset:3172
	ds_write_b32 v14, v34 offset:3176
	ds_write_b32 v14, v35 offset:3180
	s_waitcnt vmcnt(19)
	ds_write_b32 v14, v36 offset:4224
	ds_write_b32 v14, v37 offset:4228
	ds_write_b32 v14, v38 offset:4232
	ds_write_b32 v14, v39 offset:4236
	s_waitcnt vmcnt(18)
	ds_write_b32 v14, v40 offset:5280
	ds_write_b32 v14, v41 offset:5284
	ds_write_b32 v14, v42 offset:5288
	ds_write_b32 v14, v43 offset:5292
	s_waitcnt vmcnt(17)
	ds_write_b32 v14, v44 offset:6336
	ds_write_b32 v14, v45 offset:6340
	ds_write_b32 v14, v46 offset:6344
	ds_write_b32 v14, v47 offset:6348
	s_waitcnt vmcnt(16)
	ds_write_b32 v14, v48 offset:7392
	ds_write_b32 v14, v49 offset:7396
	ds_write_b32 v14, v50 offset:7400
	ds_write_b32 v14, v51 offset:7404
	s_add_u32 s95, s94, 0x2000
	s_lshr_b32 vcc_lo, s95, 7
	s_and_b32 vcc_hi, s95, 0x7f
	s_lshl_b32 vcc_lo, vcc_lo, 20
	s_lshl_b32 vcc_hi, vcc_hi, 7
	s_add_u32 s96, s100, vcc_lo
	s_addc_u32 s97, s101, 0
	s_add_u32 s96, s96, vcc_hi
	s_addc_u32 s97, s97, 0
	global_load_dwordx4 v[20:23], v6, s[96:97]
	global_load_dwordx4 v[24:27], v7, s[96:97]
	global_load_dwordx4 v[28:31], v8, s[96:97]
	global_load_dwordx4 v[32:35], v9, s[96:97]
	global_load_dwordx4 v[36:39], v10, s[96:97]
	global_load_dwordx4 v[40:43], v11, s[96:97]
	global_load_dwordx4 v[44:47], v12, s[96:97]
	global_load_dwordx4 v[48:51], v13, s[96:97]
	ds_read2_b32 v[52:53], v15 offset0:0 offset1:33
	ds_read2_b32 v[54:55], v15 offset0:66 offset1:99
	ds_read2_b32 v[56:57], v15 offset0:132 offset1:165
	ds_read2_b32 v[58:59], v15 offset0:198 offset1:231
	ds_read2_b32 v[60:61], v15 offset0:8 offset1:41
	ds_read2_b32 v[62:63], v15 offset0:74 offset1:107
	ds_read2_b32 v[64:65], v15 offset0:140 offset1:173
	ds_read2_b32 v[66:67], v15 offset0:206 offset1:239
	ds_read2_b32 v[68:69], v15 offset0:16 offset1:49
	ds_read2_b32 v[70:71], v15 offset0:82 offset1:115
	ds_read2_b32 v[72:73], v15 offset0:148 offset1:181
	ds_read2_b32 v[74:75], v15 offset0:214 offset1:247
	ds_read2_b32 v[76:77], v15 offset0:24 offset1:57
	ds_read2_b32 v[78:79], v15 offset0:90 offset1:123
	ds_read2_b32 v[80:81], v15 offset0:156 offset1:189
	ds_read2_b32 v[82:83], v15 offset0:222 offset1:255
	s_add_u32 s95, s94, 0x1800
	s_lshr_b32 vcc_lo, s95, 7
	s_and_b32 vcc_hi, s95, 0x7f
	s_mul_i32 vcc_hi, vcc_hi, 0xac000
	s_lshl_b32 vcc_lo, vcc_lo, 7
	s_add_u32 s98, s66, 0x12d00000
	s_addc_u32 s99, s67, 0
	s_add_u32 s98, s98, vcc_hi
	s_addc_u32 s99, s99, 0
	s_add_u32 s98, s98, vcc_lo
	s_addc_u32 s99, s99, 0
	s_waitcnt lgkmcnt(0)
	v_cvt_pk_bf16_f32 v84, v52, v53
	v_cvt_pk_bf16_f32 v85, v54, v55
	v_cvt_pk_bf16_f32 v86, v56, v57
	v_cvt_pk_bf16_f32 v87, v58, v59
	v_cvt_pk_bf16_f32 v88, v60, v61
	v_cvt_pk_bf16_f32 v89, v62, v63
	v_cvt_pk_bf16_f32 v90, v64, v65
	v_cvt_pk_bf16_f32 v91, v66, v67
	v_cvt_pk_bf16_f32 v92, v68, v69
	v_cvt_pk_bf16_f32 v93, v70, v71
	v_cvt_pk_bf16_f32 v94, v72, v73
	v_cvt_pk_bf16_f32 v95, v74, v75
	v_cvt_pk_bf16_f32 v96, v76, v77
	v_cvt_pk_bf16_f32 v97, v78, v79
	v_cvt_pk_bf16_f32 v98, v80, v81
	v_cvt_pk_bf16_f32 v99, v82, v83
	global_store_dwordx4 v16, v[84:87], s[98:99]
	global_store_dwordx4 v17, v[88:91], s[98:99]
	global_store_dwordx4 v18, v[92:95], s[98:99]
	global_store_dwordx4 v19, v[96:99], s[98:99]
	s_waitcnt vmcnt(23)
	ds_write_b32 v14, v100 offset:0
	ds_write_b32 v14, v101 offset:4
	ds_write_b32 v14, v102 offset:8
	ds_write_b32 v14, v103 offset:12
	s_waitcnt vmcnt(22)
	ds_write_b32 v14, v104 offset:1056
	ds_write_b32 v14, v105 offset:1060
	ds_write_b32 v14, v106 offset:1064
	ds_write_b32 v14, v107 offset:1068
	s_waitcnt vmcnt(21)
	ds_write_b32 v14, v108 offset:2112
	ds_write_b32 v14, v109 offset:2116
	ds_write_b32 v14, v110 offset:2120
	ds_write_b32 v14, v111 offset:2124
	s_waitcnt vmcnt(20)
	ds_write_b32 v14, v112 offset:3168
	ds_write_b32 v14, v113 offset:3172
	ds_write_b32 v14, v114 offset:3176
	ds_write_b32 v14, v115 offset:3180
	s_waitcnt vmcnt(19)
	ds_write_b32 v14, v116 offset:4224
	ds_write_b32 v14, v117 offset:4228
	ds_write_b32 v14, v118 offset:4232
	ds_write_b32 v14, v119 offset:4236
	s_waitcnt vmcnt(18)
	ds_write_b32 v14, v120 offset:5280
	ds_write_b32 v14, v121 offset:5284
	ds_write_b32 v14, v122 offset:5288
	ds_write_b32 v14, v123 offset:5292
	s_waitcnt vmcnt(17)
	ds_write_b32 v14, v124 offset:6336
	ds_write_b32 v14, v125 offset:6340
	ds_write_b32 v14, v126 offset:6344
	ds_write_b32 v14, v127 offset:6348
	s_waitcnt vmcnt(16)
	ds_write_b32 v14, v128 offset:7392
	ds_write_b32 v14, v129 offset:7396
	ds_write_b32 v14, v130 offset:7400
	ds_write_b32 v14, v131 offset:7404
	s_add_u32 s95, s94, 0x2400
	s_lshr_b32 vcc_lo, s95, 7
	s_and_b32 vcc_hi, s95, 0x7f
	s_lshl_b32 vcc_lo, vcc_lo, 20
	s_lshl_b32 vcc_hi, vcc_hi, 7
	s_add_u32 s96, s100, vcc_lo
	s_addc_u32 s97, s101, 0
	s_add_u32 s96, s96, vcc_hi
	s_addc_u32 s97, s97, 0
	global_load_dwordx4 v[100:103], v6, s[96:97]
	global_load_dwordx4 v[104:107], v7, s[96:97]
	global_load_dwordx4 v[108:111], v8, s[96:97]
	global_load_dwordx4 v[112:115], v9, s[96:97]
	global_load_dwordx4 v[116:119], v10, s[96:97]
	global_load_dwordx4 v[120:123], v11, s[96:97]
	global_load_dwordx4 v[124:127], v12, s[96:97]
	global_load_dwordx4 v[128:131], v13, s[96:97]
	ds_read2_b32 v[52:53], v15 offset0:0 offset1:33
	ds_read2_b32 v[54:55], v15 offset0:66 offset1:99
	ds_read2_b32 v[56:57], v15 offset0:132 offset1:165
	ds_read2_b32 v[58:59], v15 offset0:198 offset1:231
	ds_read2_b32 v[60:61], v15 offset0:8 offset1:41
	ds_read2_b32 v[62:63], v15 offset0:74 offset1:107
	ds_read2_b32 v[64:65], v15 offset0:140 offset1:173
	ds_read2_b32 v[66:67], v15 offset0:206 offset1:239
	ds_read2_b32 v[68:69], v15 offset0:16 offset1:49
	ds_read2_b32 v[70:71], v15 offset0:82 offset1:115
	ds_read2_b32 v[72:73], v15 offset0:148 offset1:181
	ds_read2_b32 v[74:75], v15 offset0:214 offset1:247
	ds_read2_b32 v[76:77], v15 offset0:24 offset1:57
	ds_read2_b32 v[78:79], v15 offset0:90 offset1:123
	ds_read2_b32 v[80:81], v15 offset0:156 offset1:189
	ds_read2_b32 v[82:83], v15 offset0:222 offset1:255
	s_add_u32 s95, s94, 0x1c00
	s_lshr_b32 vcc_lo, s95, 7
	s_and_b32 vcc_hi, s95, 0x7f
	s_mul_i32 vcc_hi, vcc_hi, 0xac000
	s_lshl_b32 vcc_lo, vcc_lo, 7
	s_add_u32 s98, s66, 0x12d00000
	s_addc_u32 s99, s67, 0
	s_add_u32 s98, s98, vcc_hi
	s_addc_u32 s99, s99, 0
	s_add_u32 s98, s98, vcc_lo
	s_addc_u32 s99, s99, 0
	s_waitcnt lgkmcnt(0)
	v_cvt_pk_bf16_f32 v84, v52, v53
	v_cvt_pk_bf16_f32 v85, v54, v55
	v_cvt_pk_bf16_f32 v86, v56, v57
	v_cvt_pk_bf16_f32 v87, v58, v59
	v_cvt_pk_bf16_f32 v88, v60, v61
	v_cvt_pk_bf16_f32 v89, v62, v63
	v_cvt_pk_bf16_f32 v90, v64, v65
	v_cvt_pk_bf16_f32 v91, v66, v67
	v_cvt_pk_bf16_f32 v92, v68, v69
	v_cvt_pk_bf16_f32 v93, v70, v71
	v_cvt_pk_bf16_f32 v94, v72, v73
	v_cvt_pk_bf16_f32 v95, v74, v75
	v_cvt_pk_bf16_f32 v96, v76, v77
	v_cvt_pk_bf16_f32 v97, v78, v79
	v_cvt_pk_bf16_f32 v98, v80, v81
	v_cvt_pk_bf16_f32 v99, v82, v83
	global_store_dwordx4 v16, v[84:87], s[98:99]
	global_store_dwordx4 v17, v[88:91], s[98:99]
	global_store_dwordx4 v18, v[92:95], s[98:99]
	global_store_dwordx4 v19, v[96:99], s[98:99]
	s_waitcnt vmcnt(23)
	ds_write_b32 v14, v20 offset:0
	ds_write_b32 v14, v21 offset:4
	ds_write_b32 v14, v22 offset:8
	ds_write_b32 v14, v23 offset:12
	s_waitcnt vmcnt(22)
	ds_write_b32 v14, v24 offset:1056
	ds_write_b32 v14, v25 offset:1060
	ds_write_b32 v14, v26 offset:1064
	ds_write_b32 v14, v27 offset:1068
	s_waitcnt vmcnt(21)
	ds_write_b32 v14, v28 offset:2112
	ds_write_b32 v14, v29 offset:2116
	ds_write_b32 v14, v30 offset:2120
	ds_write_b32 v14, v31 offset:2124
	s_waitcnt vmcnt(20)
	ds_write_b32 v14, v32 offset:3168
	ds_write_b32 v14, v33 offset:3172
	ds_write_b32 v14, v34 offset:3176
	ds_write_b32 v14, v35 offset:3180
	s_waitcnt vmcnt(19)
	ds_write_b32 v14, v36 offset:4224
	ds_write_b32 v14, v37 offset:4228
	ds_write_b32 v14, v38 offset:4232
	ds_write_b32 v14, v39 offset:4236
	s_waitcnt vmcnt(18)
	ds_write_b32 v14, v40 offset:5280
	ds_write_b32 v14, v41 offset:5284
	ds_write_b32 v14, v42 offset:5288
	ds_write_b32 v14, v43 offset:5292
	s_waitcnt vmcnt(17)
	ds_write_b32 v14, v44 offset:6336
	ds_write_b32 v14, v45 offset:6340
	ds_write_b32 v14, v46 offset:6344
	ds_write_b32 v14, v47 offset:6348
	s_waitcnt vmcnt(16)
	ds_write_b32 v14, v48 offset:7392
	ds_write_b32 v14, v49 offset:7396
	ds_write_b32 v14, v50 offset:7400
	ds_write_b32 v14, v51 offset:7404
	s_add_u32 s95, s94, 0x2800
	s_lshr_b32 vcc_lo, s95, 7
	s_and_b32 vcc_hi, s95, 0x7f
	s_lshl_b32 vcc_lo, vcc_lo, 20
	s_lshl_b32 vcc_hi, vcc_hi, 7
	s_add_u32 s96, s100, vcc_lo
	s_addc_u32 s97, s101, 0
	s_add_u32 s96, s96, vcc_hi
	s_addc_u32 s97, s97, 0
	global_load_dwordx4 v[20:23], v6, s[96:97]
	global_load_dwordx4 v[24:27], v7, s[96:97]
	global_load_dwordx4 v[28:31], v8, s[96:97]
	global_load_dwordx4 v[32:35], v9, s[96:97]
	global_load_dwordx4 v[36:39], v10, s[96:97]
	global_load_dwordx4 v[40:43], v11, s[96:97]
	global_load_dwordx4 v[44:47], v12, s[96:97]
	global_load_dwordx4 v[48:51], v13, s[96:97]
	ds_read2_b32 v[52:53], v15 offset0:0 offset1:33
	ds_read2_b32 v[54:55], v15 offset0:66 offset1:99
	ds_read2_b32 v[56:57], v15 offset0:132 offset1:165
	ds_read2_b32 v[58:59], v15 offset0:198 offset1:231
	ds_read2_b32 v[60:61], v15 offset0:8 offset1:41
	ds_read2_b32 v[62:63], v15 offset0:74 offset1:107
	ds_read2_b32 v[64:65], v15 offset0:140 offset1:173
	ds_read2_b32 v[66:67], v15 offset0:206 offset1:239
	ds_read2_b32 v[68:69], v15 offset0:16 offset1:49
	ds_read2_b32 v[70:71], v15 offset0:82 offset1:115
	ds_read2_b32 v[72:73], v15 offset0:148 offset1:181
	ds_read2_b32 v[74:75], v15 offset0:214 offset1:247
	ds_read2_b32 v[76:77], v15 offset0:24 offset1:57
	ds_read2_b32 v[78:79], v15 offset0:90 offset1:123
	ds_read2_b32 v[80:81], v15 offset0:156 offset1:189
	ds_read2_b32 v[82:83], v15 offset0:222 offset1:255
	s_add_u32 s95, s94, 0x2000
	s_lshr_b32 vcc_lo, s95, 7
	s_and_b32 vcc_hi, s95, 0x7f
	s_mul_i32 vcc_hi, vcc_hi, 0xac000
	s_lshl_b32 vcc_lo, vcc_lo, 7
	s_add_u32 s98, s66, 0x12d00000
	s_addc_u32 s99, s67, 0
	s_add_u32 s98, s98, vcc_hi
	s_addc_u32 s99, s99, 0
	s_add_u32 s98, s98, vcc_lo
	s_addc_u32 s99, s99, 0
	s_waitcnt lgkmcnt(0)
	v_cvt_pk_bf16_f32 v84, v52, v53
	v_cvt_pk_bf16_f32 v85, v54, v55
	v_cvt_pk_bf16_f32 v86, v56, v57
	v_cvt_pk_bf16_f32 v87, v58, v59
	v_cvt_pk_bf16_f32 v88, v60, v61
	v_cvt_pk_bf16_f32 v89, v62, v63
	v_cvt_pk_bf16_f32 v90, v64, v65
	v_cvt_pk_bf16_f32 v91, v66, v67
	v_cvt_pk_bf16_f32 v92, v68, v69
	v_cvt_pk_bf16_f32 v93, v70, v71
	v_cvt_pk_bf16_f32 v94, v72, v73
	v_cvt_pk_bf16_f32 v95, v74, v75
	v_cvt_pk_bf16_f32 v96, v76, v77
	v_cvt_pk_bf16_f32 v97, v78, v79
	v_cvt_pk_bf16_f32 v98, v80, v81
	v_cvt_pk_bf16_f32 v99, v82, v83
	global_store_dwordx4 v16, v[84:87], s[98:99]
	global_store_dwordx4 v17, v[88:91], s[98:99]
	global_store_dwordx4 v18, v[92:95], s[98:99]
	global_store_dwordx4 v19, v[96:99], s[98:99]
	s_waitcnt vmcnt(23)
	ds_write_b32 v14, v100 offset:0
	ds_write_b32 v14, v101 offset:4
	ds_write_b32 v14, v102 offset:8
	ds_write_b32 v14, v103 offset:12
	s_waitcnt vmcnt(22)
	ds_write_b32 v14, v104 offset:1056
	ds_write_b32 v14, v105 offset:1060
	ds_write_b32 v14, v106 offset:1064
	ds_write_b32 v14, v107 offset:1068
	s_waitcnt vmcnt(21)
	ds_write_b32 v14, v108 offset:2112
	ds_write_b32 v14, v109 offset:2116
	ds_write_b32 v14, v110 offset:2120
	ds_write_b32 v14, v111 offset:2124
	s_waitcnt vmcnt(20)
	ds_write_b32 v14, v112 offset:3168
	ds_write_b32 v14, v113 offset:3172
	ds_write_b32 v14, v114 offset:3176
	ds_write_b32 v14, v115 offset:3180
	s_waitcnt vmcnt(19)
	ds_write_b32 v14, v116 offset:4224
	ds_write_b32 v14, v117 offset:4228
	ds_write_b32 v14, v118 offset:4232
	ds_write_b32 v14, v119 offset:4236
	s_waitcnt vmcnt(18)
	ds_write_b32 v14, v120 offset:5280
	ds_write_b32 v14, v121 offset:5284
	ds_write_b32 v14, v122 offset:5288
	ds_write_b32 v14, v123 offset:5292
	s_waitcnt vmcnt(17)
	ds_write_b32 v14, v124 offset:6336
	ds_write_b32 v14, v125 offset:6340
	ds_write_b32 v14, v126 offset:6344
	ds_write_b32 v14, v127 offset:6348
	s_waitcnt vmcnt(16)
	ds_write_b32 v14, v128 offset:7392
	ds_write_b32 v14, v129 offset:7396
	ds_write_b32 v14, v130 offset:7400
	ds_write_b32 v14, v131 offset:7404
	s_add_u32 s95, s94, 0x2c00
	s_lshr_b32 vcc_lo, s95, 7
	s_and_b32 vcc_hi, s95, 0x7f
	s_lshl_b32 vcc_lo, vcc_lo, 20
	s_lshl_b32 vcc_hi, vcc_hi, 7
	s_add_u32 s96, s100, vcc_lo
	s_addc_u32 s97, s101, 0
	s_add_u32 s96, s96, vcc_hi
	s_addc_u32 s97, s97, 0
	global_load_dwordx4 v[100:103], v6, s[96:97]
	global_load_dwordx4 v[104:107], v7, s[96:97]
	global_load_dwordx4 v[108:111], v8, s[96:97]
	global_load_dwordx4 v[112:115], v9, s[96:97]
	global_load_dwordx4 v[116:119], v10, s[96:97]
	global_load_dwordx4 v[120:123], v11, s[96:97]
	global_load_dwordx4 v[124:127], v12, s[96:97]
	global_load_dwordx4 v[128:131], v13, s[96:97]
	ds_read2_b32 v[52:53], v15 offset0:0 offset1:33
	ds_read2_b32 v[54:55], v15 offset0:66 offset1:99
	ds_read2_b32 v[56:57], v15 offset0:132 offset1:165
	ds_read2_b32 v[58:59], v15 offset0:198 offset1:231
	ds_read2_b32 v[60:61], v15 offset0:8 offset1:41
	ds_read2_b32 v[62:63], v15 offset0:74 offset1:107
	ds_read2_b32 v[64:65], v15 offset0:140 offset1:173
	ds_read2_b32 v[66:67], v15 offset0:206 offset1:239
	ds_read2_b32 v[68:69], v15 offset0:16 offset1:49
	ds_read2_b32 v[70:71], v15 offset0:82 offset1:115
	ds_read2_b32 v[72:73], v15 offset0:148 offset1:181
	ds_read2_b32 v[74:75], v15 offset0:214 offset1:247
	ds_read2_b32 v[76:77], v15 offset0:24 offset1:57
	ds_read2_b32 v[78:79], v15 offset0:90 offset1:123
	ds_read2_b32 v[80:81], v15 offset0:156 offset1:189
	ds_read2_b32 v[82:83], v15 offset0:222 offset1:255
	s_add_u32 s95, s94, 0x2400
	s_lshr_b32 vcc_lo, s95, 7
	s_and_b32 vcc_hi, s95, 0x7f
	s_mul_i32 vcc_hi, vcc_hi, 0xac000
	s_lshl_b32 vcc_lo, vcc_lo, 7
	s_add_u32 s98, s66, 0x12d00000
	s_addc_u32 s99, s67, 0
	s_add_u32 s98, s98, vcc_hi
	s_addc_u32 s99, s99, 0
	s_add_u32 s98, s98, vcc_lo
	s_addc_u32 s99, s99, 0
	s_waitcnt lgkmcnt(0)
	v_cvt_pk_bf16_f32 v84, v52, v53
	v_cvt_pk_bf16_f32 v85, v54, v55
	v_cvt_pk_bf16_f32 v86, v56, v57
	v_cvt_pk_bf16_f32 v87, v58, v59
	v_cvt_pk_bf16_f32 v88, v60, v61
	v_cvt_pk_bf16_f32 v89, v62, v63
	v_cvt_pk_bf16_f32 v90, v64, v65
	v_cvt_pk_bf16_f32 v91, v66, v67
	v_cvt_pk_bf16_f32 v92, v68, v69
	v_cvt_pk_bf16_f32 v93, v70, v71
	v_cvt_pk_bf16_f32 v94, v72, v73
	v_cvt_pk_bf16_f32 v95, v74, v75
	v_cvt_pk_bf16_f32 v96, v76, v77
	v_cvt_pk_bf16_f32 v97, v78, v79
	v_cvt_pk_bf16_f32 v98, v80, v81
	v_cvt_pk_bf16_f32 v99, v82, v83
	global_store_dwordx4 v16, v[84:87], s[98:99]
	global_store_dwordx4 v17, v[88:91], s[98:99]
	global_store_dwordx4 v18, v[92:95], s[98:99]
	global_store_dwordx4 v19, v[96:99], s[98:99]
	s_waitcnt vmcnt(23)
	ds_write_b32 v14, v20 offset:0
	ds_write_b32 v14, v21 offset:4
	ds_write_b32 v14, v22 offset:8
	ds_write_b32 v14, v23 offset:12
	s_waitcnt vmcnt(22)
	ds_write_b32 v14, v24 offset:1056
	ds_write_b32 v14, v25 offset:1060
	ds_write_b32 v14, v26 offset:1064
	ds_write_b32 v14, v27 offset:1068
	s_waitcnt vmcnt(21)
	ds_write_b32 v14, v28 offset:2112
	ds_write_b32 v14, v29 offset:2116
	ds_write_b32 v14, v30 offset:2120
	ds_write_b32 v14, v31 offset:2124
	s_waitcnt vmcnt(20)
	ds_write_b32 v14, v32 offset:3168
	ds_write_b32 v14, v33 offset:3172
	ds_write_b32 v14, v34 offset:3176
	ds_write_b32 v14, v35 offset:3180
	s_waitcnt vmcnt(19)
	ds_write_b32 v14, v36 offset:4224
	ds_write_b32 v14, v37 offset:4228
	ds_write_b32 v14, v38 offset:4232
	ds_write_b32 v14, v39 offset:4236
	s_waitcnt vmcnt(18)
	ds_write_b32 v14, v40 offset:5280
	ds_write_b32 v14, v41 offset:5284
	ds_write_b32 v14, v42 offset:5288
	ds_write_b32 v14, v43 offset:5292
	s_waitcnt vmcnt(17)
	ds_write_b32 v14, v44 offset:6336
	ds_write_b32 v14, v45 offset:6340
	ds_write_b32 v14, v46 offset:6344
	ds_write_b32 v14, v47 offset:6348
	s_waitcnt vmcnt(16)
	ds_write_b32 v14, v48 offset:7392
	ds_write_b32 v14, v49 offset:7396
	ds_write_b32 v14, v50 offset:7400
	ds_write_b32 v14, v51 offset:7404
	s_add_u32 s95, s94, 0x3000
	s_lshr_b32 vcc_lo, s95, 7
	s_and_b32 vcc_hi, s95, 0x7f
	s_lshl_b32 vcc_lo, vcc_lo, 20
	s_lshl_b32 vcc_hi, vcc_hi, 7
	s_add_u32 s96, s100, vcc_lo
	s_addc_u32 s97, s101, 0
	s_add_u32 s96, s96, vcc_hi
	s_addc_u32 s97, s97, 0
	global_load_dwordx4 v[20:23], v6, s[96:97]
	global_load_dwordx4 v[24:27], v7, s[96:97]
	global_load_dwordx4 v[28:31], v8, s[96:97]
	global_load_dwordx4 v[32:35], v9, s[96:97]
	global_load_dwordx4 v[36:39], v10, s[96:97]
	global_load_dwordx4 v[40:43], v11, s[96:97]
	global_load_dwordx4 v[44:47], v12, s[96:97]
	global_load_dwordx4 v[48:51], v13, s[96:97]
	ds_read2_b32 v[52:53], v15 offset0:0 offset1:33
	ds_read2_b32 v[54:55], v15 offset0:66 offset1:99
	ds_read2_b32 v[56:57], v15 offset0:132 offset1:165
	ds_read2_b32 v[58:59], v15 offset0:198 offset1:231
	ds_read2_b32 v[60:61], v15 offset0:8 offset1:41
	ds_read2_b32 v[62:63], v15 offset0:74 offset1:107
	ds_read2_b32 v[64:65], v15 offset0:140 offset1:173
	ds_read2_b32 v[66:67], v15 offset0:206 offset1:239
	ds_read2_b32 v[68:69], v15 offset0:16 offset1:49
	ds_read2_b32 v[70:71], v15 offset0:82 offset1:115
	ds_read2_b32 v[72:73], v15 offset0:148 offset1:181
	ds_read2_b32 v[74:75], v15 offset0:214 offset1:247
	ds_read2_b32 v[76:77], v15 offset0:24 offset1:57
	ds_read2_b32 v[78:79], v15 offset0:90 offset1:123
	ds_read2_b32 v[80:81], v15 offset0:156 offset1:189
	ds_read2_b32 v[82:83], v15 offset0:222 offset1:255
	s_add_u32 s95, s94, 0x2800
	s_lshr_b32 vcc_lo, s95, 7
	s_and_b32 vcc_hi, s95, 0x7f
	s_mul_i32 vcc_hi, vcc_hi, 0xac000
	s_lshl_b32 vcc_lo, vcc_lo, 7
	s_add_u32 s98, s66, 0x12d00000
	s_addc_u32 s99, s67, 0
	s_add_u32 s98, s98, vcc_hi
	s_addc_u32 s99, s99, 0
	s_add_u32 s98, s98, vcc_lo
	s_addc_u32 s99, s99, 0
	s_waitcnt lgkmcnt(0)
	v_cvt_pk_bf16_f32 v84, v52, v53
	v_cvt_pk_bf16_f32 v85, v54, v55
	v_cvt_pk_bf16_f32 v86, v56, v57
	v_cvt_pk_bf16_f32 v87, v58, v59
	v_cvt_pk_bf16_f32 v88, v60, v61
	v_cvt_pk_bf16_f32 v89, v62, v63
	v_cvt_pk_bf16_f32 v90, v64, v65
	v_cvt_pk_bf16_f32 v91, v66, v67
	v_cvt_pk_bf16_f32 v92, v68, v69
	v_cvt_pk_bf16_f32 v93, v70, v71
	v_cvt_pk_bf16_f32 v94, v72, v73
	v_cvt_pk_bf16_f32 v95, v74, v75
	v_cvt_pk_bf16_f32 v96, v76, v77
	v_cvt_pk_bf16_f32 v97, v78, v79
	v_cvt_pk_bf16_f32 v98, v80, v81
	v_cvt_pk_bf16_f32 v99, v82, v83
	global_store_dwordx4 v16, v[84:87], s[98:99]
	global_store_dwordx4 v17, v[88:91], s[98:99]
	global_store_dwordx4 v18, v[92:95], s[98:99]
	global_store_dwordx4 v19, v[96:99], s[98:99]
	s_waitcnt vmcnt(23)
	ds_write_b32 v14, v100 offset:0
	ds_write_b32 v14, v101 offset:4
	ds_write_b32 v14, v102 offset:8
	ds_write_b32 v14, v103 offset:12
	s_waitcnt vmcnt(22)
	ds_write_b32 v14, v104 offset:1056
	ds_write_b32 v14, v105 offset:1060
	ds_write_b32 v14, v106 offset:1064
	ds_write_b32 v14, v107 offset:1068
	s_waitcnt vmcnt(21)
	ds_write_b32 v14, v108 offset:2112
	ds_write_b32 v14, v109 offset:2116
	ds_write_b32 v14, v110 offset:2120
	ds_write_b32 v14, v111 offset:2124
	s_waitcnt vmcnt(20)
	ds_write_b32 v14, v112 offset:3168
	ds_write_b32 v14, v113 offset:3172
	ds_write_b32 v14, v114 offset:3176
	ds_write_b32 v14, v115 offset:3180
	s_waitcnt vmcnt(19)
	ds_write_b32 v14, v116 offset:4224
	ds_write_b32 v14, v117 offset:4228
	ds_write_b32 v14, v118 offset:4232
	ds_write_b32 v14, v119 offset:4236
	s_waitcnt vmcnt(18)
	ds_write_b32 v14, v120 offset:5280
	ds_write_b32 v14, v121 offset:5284
	ds_write_b32 v14, v122 offset:5288
	ds_write_b32 v14, v123 offset:5292
	s_waitcnt vmcnt(17)
	ds_write_b32 v14, v124 offset:6336
	ds_write_b32 v14, v125 offset:6340
	ds_write_b32 v14, v126 offset:6344
	ds_write_b32 v14, v127 offset:6348
	s_waitcnt vmcnt(16)
	ds_write_b32 v14, v128 offset:7392
	ds_write_b32 v14, v129 offset:7396
	ds_write_b32 v14, v130 offset:7400
	ds_write_b32 v14, v131 offset:7404
	s_add_u32 s95, s94, 0x3400
	s_lshr_b32 vcc_lo, s95, 7
	s_and_b32 vcc_hi, s95, 0x7f
	s_lshl_b32 vcc_lo, vcc_lo, 20
	s_lshl_b32 vcc_hi, vcc_hi, 7
	s_add_u32 s96, s100, vcc_lo
	s_addc_u32 s97, s101, 0
	s_add_u32 s96, s96, vcc_hi
	s_addc_u32 s97, s97, 0
	global_load_dwordx4 v[100:103], v6, s[96:97]
	global_load_dwordx4 v[104:107], v7, s[96:97]
	global_load_dwordx4 v[108:111], v8, s[96:97]
	global_load_dwordx4 v[112:115], v9, s[96:97]
	global_load_dwordx4 v[116:119], v10, s[96:97]
	global_load_dwordx4 v[120:123], v11, s[96:97]
	global_load_dwordx4 v[124:127], v12, s[96:97]
	global_load_dwordx4 v[128:131], v13, s[96:97]
	ds_read2_b32 v[52:53], v15 offset0:0 offset1:33
	ds_read2_b32 v[54:55], v15 offset0:66 offset1:99
	ds_read2_b32 v[56:57], v15 offset0:132 offset1:165
	ds_read2_b32 v[58:59], v15 offset0:198 offset1:231
	ds_read2_b32 v[60:61], v15 offset0:8 offset1:41
	ds_read2_b32 v[62:63], v15 offset0:74 offset1:107
	ds_read2_b32 v[64:65], v15 offset0:140 offset1:173
	ds_read2_b32 v[66:67], v15 offset0:206 offset1:239
	ds_read2_b32 v[68:69], v15 offset0:16 offset1:49
	ds_read2_b32 v[70:71], v15 offset0:82 offset1:115
	ds_read2_b32 v[72:73], v15 offset0:148 offset1:181
	ds_read2_b32 v[74:75], v15 offset0:214 offset1:247
	ds_read2_b32 v[76:77], v15 offset0:24 offset1:57
	ds_read2_b32 v[78:79], v15 offset0:90 offset1:123
	ds_read2_b32 v[80:81], v15 offset0:156 offset1:189
	ds_read2_b32 v[82:83], v15 offset0:222 offset1:255
	s_add_u32 s95, s94, 0x2c00
	s_lshr_b32 vcc_lo, s95, 7
	s_and_b32 vcc_hi, s95, 0x7f
	s_mul_i32 vcc_hi, vcc_hi, 0xac000
	s_lshl_b32 vcc_lo, vcc_lo, 7
	s_add_u32 s98, s66, 0x12d00000
	s_addc_u32 s99, s67, 0
	s_add_u32 s98, s98, vcc_hi
	s_addc_u32 s99, s99, 0
	s_add_u32 s98, s98, vcc_lo
	s_addc_u32 s99, s99, 0
	s_waitcnt lgkmcnt(0)
	v_cvt_pk_bf16_f32 v84, v52, v53
	v_cvt_pk_bf16_f32 v85, v54, v55
	v_cvt_pk_bf16_f32 v86, v56, v57
	v_cvt_pk_bf16_f32 v87, v58, v59
	v_cvt_pk_bf16_f32 v88, v60, v61
	v_cvt_pk_bf16_f32 v89, v62, v63
	v_cvt_pk_bf16_f32 v90, v64, v65
	v_cvt_pk_bf16_f32 v91, v66, v67
	v_cvt_pk_bf16_f32 v92, v68, v69
	v_cvt_pk_bf16_f32 v93, v70, v71
	v_cvt_pk_bf16_f32 v94, v72, v73
	v_cvt_pk_bf16_f32 v95, v74, v75
	v_cvt_pk_bf16_f32 v96, v76, v77
	v_cvt_pk_bf16_f32 v97, v78, v79
	v_cvt_pk_bf16_f32 v98, v80, v81
	v_cvt_pk_bf16_f32 v99, v82, v83
	global_store_dwordx4 v16, v[84:87], s[98:99]
	global_store_dwordx4 v17, v[88:91], s[98:99]
	global_store_dwordx4 v18, v[92:95], s[98:99]
	global_store_dwordx4 v19, v[96:99], s[98:99]
	s_waitcnt vmcnt(23)
	ds_write_b32 v14, v20 offset:0
	ds_write_b32 v14, v21 offset:4
	ds_write_b32 v14, v22 offset:8
	ds_write_b32 v14, v23 offset:12
	s_waitcnt vmcnt(22)
	ds_write_b32 v14, v24 offset:1056
	ds_write_b32 v14, v25 offset:1060
	ds_write_b32 v14, v26 offset:1064
	ds_write_b32 v14, v27 offset:1068
	s_waitcnt vmcnt(21)
	ds_write_b32 v14, v28 offset:2112
	ds_write_b32 v14, v29 offset:2116
	ds_write_b32 v14, v30 offset:2120
	ds_write_b32 v14, v31 offset:2124
	s_waitcnt vmcnt(20)
	ds_write_b32 v14, v32 offset:3168
	ds_write_b32 v14, v33 offset:3172
	ds_write_b32 v14, v34 offset:3176
	ds_write_b32 v14, v35 offset:3180
	s_waitcnt vmcnt(19)
	ds_write_b32 v14, v36 offset:4224
	ds_write_b32 v14, v37 offset:4228
	ds_write_b32 v14, v38 offset:4232
	ds_write_b32 v14, v39 offset:4236
	s_waitcnt vmcnt(18)
	ds_write_b32 v14, v40 offset:5280
	ds_write_b32 v14, v41 offset:5284
	ds_write_b32 v14, v42 offset:5288
	ds_write_b32 v14, v43 offset:5292
	s_waitcnt vmcnt(17)
	ds_write_b32 v14, v44 offset:6336
	ds_write_b32 v14, v45 offset:6340
	ds_write_b32 v14, v46 offset:6344
	ds_write_b32 v14, v47 offset:6348
	s_waitcnt vmcnt(16)
	ds_write_b32 v14, v48 offset:7392
	ds_write_b32 v14, v49 offset:7396
	ds_write_b32 v14, v50 offset:7400
	ds_write_b32 v14, v51 offset:7404
	s_add_u32 s95, s94, 0x3800
	s_lshr_b32 vcc_lo, s95, 7
	s_and_b32 vcc_hi, s95, 0x7f
	s_lshl_b32 vcc_lo, vcc_lo, 20
	s_lshl_b32 vcc_hi, vcc_hi, 7
	s_add_u32 s96, s100, vcc_lo
	s_addc_u32 s97, s101, 0
	s_add_u32 s96, s96, vcc_hi
	s_addc_u32 s97, s97, 0
	global_load_dwordx4 v[20:23], v6, s[96:97]
	global_load_dwordx4 v[24:27], v7, s[96:97]
	global_load_dwordx4 v[28:31], v8, s[96:97]
	global_load_dwordx4 v[32:35], v9, s[96:97]
	global_load_dwordx4 v[36:39], v10, s[96:97]
	global_load_dwordx4 v[40:43], v11, s[96:97]
	global_load_dwordx4 v[44:47], v12, s[96:97]
	global_load_dwordx4 v[48:51], v13, s[96:97]
	ds_read2_b32 v[52:53], v15 offset0:0 offset1:33
	ds_read2_b32 v[54:55], v15 offset0:66 offset1:99
	ds_read2_b32 v[56:57], v15 offset0:132 offset1:165
	ds_read2_b32 v[58:59], v15 offset0:198 offset1:231
	ds_read2_b32 v[60:61], v15 offset0:8 offset1:41
	ds_read2_b32 v[62:63], v15 offset0:74 offset1:107
	ds_read2_b32 v[64:65], v15 offset0:140 offset1:173
	ds_read2_b32 v[66:67], v15 offset0:206 offset1:239
	ds_read2_b32 v[68:69], v15 offset0:16 offset1:49
	ds_read2_b32 v[70:71], v15 offset0:82 offset1:115
	ds_read2_b32 v[72:73], v15 offset0:148 offset1:181
	ds_read2_b32 v[74:75], v15 offset0:214 offset1:247
	ds_read2_b32 v[76:77], v15 offset0:24 offset1:57
	ds_read2_b32 v[78:79], v15 offset0:90 offset1:123
	ds_read2_b32 v[80:81], v15 offset0:156 offset1:189
	ds_read2_b32 v[82:83], v15 offset0:222 offset1:255
	s_add_u32 s95, s94, 0x3000
	s_lshr_b32 vcc_lo, s95, 7
	s_and_b32 vcc_hi, s95, 0x7f
	s_mul_i32 vcc_hi, vcc_hi, 0xac000
	s_lshl_b32 vcc_lo, vcc_lo, 7
	s_add_u32 s98, s66, 0x12d00000
	s_addc_u32 s99, s67, 0
	s_add_u32 s98, s98, vcc_hi
	s_addc_u32 s99, s99, 0
	s_add_u32 s98, s98, vcc_lo
	s_addc_u32 s99, s99, 0
	s_waitcnt lgkmcnt(0)
	v_cvt_pk_bf16_f32 v84, v52, v53
	v_cvt_pk_bf16_f32 v85, v54, v55
	v_cvt_pk_bf16_f32 v86, v56, v57
	v_cvt_pk_bf16_f32 v87, v58, v59
	v_cvt_pk_bf16_f32 v88, v60, v61
	v_cvt_pk_bf16_f32 v89, v62, v63
	v_cvt_pk_bf16_f32 v90, v64, v65
	v_cvt_pk_bf16_f32 v91, v66, v67
	v_cvt_pk_bf16_f32 v92, v68, v69
	v_cvt_pk_bf16_f32 v93, v70, v71
	v_cvt_pk_bf16_f32 v94, v72, v73
	v_cvt_pk_bf16_f32 v95, v74, v75
	v_cvt_pk_bf16_f32 v96, v76, v77
	v_cvt_pk_bf16_f32 v97, v78, v79
	v_cvt_pk_bf16_f32 v98, v80, v81
	v_cvt_pk_bf16_f32 v99, v82, v83
	global_store_dwordx4 v16, v[84:87], s[98:99]
	global_store_dwordx4 v17, v[88:91], s[98:99]
	global_store_dwordx4 v18, v[92:95], s[98:99]
	global_store_dwordx4 v19, v[96:99], s[98:99]
	s_waitcnt vmcnt(23)
	ds_write_b32 v14, v100 offset:0
	ds_write_b32 v14, v101 offset:4
	ds_write_b32 v14, v102 offset:8
	ds_write_b32 v14, v103 offset:12
	s_waitcnt vmcnt(22)
	ds_write_b32 v14, v104 offset:1056
	ds_write_b32 v14, v105 offset:1060
	ds_write_b32 v14, v106 offset:1064
	ds_write_b32 v14, v107 offset:1068
	s_waitcnt vmcnt(21)
	ds_write_b32 v14, v108 offset:2112
	ds_write_b32 v14, v109 offset:2116
	ds_write_b32 v14, v110 offset:2120
	ds_write_b32 v14, v111 offset:2124
	s_waitcnt vmcnt(20)
	ds_write_b32 v14, v112 offset:3168
	ds_write_b32 v14, v113 offset:3172
	ds_write_b32 v14, v114 offset:3176
	ds_write_b32 v14, v115 offset:3180
	s_waitcnt vmcnt(19)
	ds_write_b32 v14, v116 offset:4224
	ds_write_b32 v14, v117 offset:4228
	ds_write_b32 v14, v118 offset:4232
	ds_write_b32 v14, v119 offset:4236
	s_waitcnt vmcnt(18)
	ds_write_b32 v14, v120 offset:5280
	ds_write_b32 v14, v121 offset:5284
	ds_write_b32 v14, v122 offset:5288
	ds_write_b32 v14, v123 offset:5292
	s_waitcnt vmcnt(17)
	ds_write_b32 v14, v124 offset:6336
	ds_write_b32 v14, v125 offset:6340
	ds_write_b32 v14, v126 offset:6344
	ds_write_b32 v14, v127 offset:6348
	s_waitcnt vmcnt(16)
	ds_write_b32 v14, v128 offset:7392
	ds_write_b32 v14, v129 offset:7396
	ds_write_b32 v14, v130 offset:7400
	ds_write_b32 v14, v131 offset:7404
	s_add_u32 s95, s94, 0x3c00
	s_lshr_b32 vcc_lo, s95, 7
	s_and_b32 vcc_hi, s95, 0x7f
	s_lshl_b32 vcc_lo, vcc_lo, 20
	s_lshl_b32 vcc_hi, vcc_hi, 7
	s_add_u32 s96, s100, vcc_lo
	s_addc_u32 s97, s101, 0
	s_add_u32 s96, s96, vcc_hi
	s_addc_u32 s97, s97, 0
	global_load_dwordx4 v[100:103], v6, s[96:97]
	global_load_dwordx4 v[104:107], v7, s[96:97]
	global_load_dwordx4 v[108:111], v8, s[96:97]
	global_load_dwordx4 v[112:115], v9, s[96:97]
	global_load_dwordx4 v[116:119], v10, s[96:97]
	global_load_dwordx4 v[120:123], v11, s[96:97]
	global_load_dwordx4 v[124:127], v12, s[96:97]
	global_load_dwordx4 v[128:131], v13, s[96:97]
	ds_read2_b32 v[52:53], v15 offset0:0 offset1:33
	ds_read2_b32 v[54:55], v15 offset0:66 offset1:99
	ds_read2_b32 v[56:57], v15 offset0:132 offset1:165
	ds_read2_b32 v[58:59], v15 offset0:198 offset1:231
	ds_read2_b32 v[60:61], v15 offset0:8 offset1:41
	ds_read2_b32 v[62:63], v15 offset0:74 offset1:107
	ds_read2_b32 v[64:65], v15 offset0:140 offset1:173
	ds_read2_b32 v[66:67], v15 offset0:206 offset1:239
	ds_read2_b32 v[68:69], v15 offset0:16 offset1:49
	ds_read2_b32 v[70:71], v15 offset0:82 offset1:115
	ds_read2_b32 v[72:73], v15 offset0:148 offset1:181
	ds_read2_b32 v[74:75], v15 offset0:214 offset1:247
	ds_read2_b32 v[76:77], v15 offset0:24 offset1:57
	ds_read2_b32 v[78:79], v15 offset0:90 offset1:123
	ds_read2_b32 v[80:81], v15 offset0:156 offset1:189
	ds_read2_b32 v[82:83], v15 offset0:222 offset1:255
	s_add_u32 s95, s94, 0x3400
	s_lshr_b32 vcc_lo, s95, 7
	s_and_b32 vcc_hi, s95, 0x7f
	s_mul_i32 vcc_hi, vcc_hi, 0xac000
	s_lshl_b32 vcc_lo, vcc_lo, 7
	s_add_u32 s98, s66, 0x12d00000
	s_addc_u32 s99, s67, 0
	s_add_u32 s98, s98, vcc_hi
	s_addc_u32 s99, s99, 0
	s_add_u32 s98, s98, vcc_lo
	s_addc_u32 s99, s99, 0
	s_waitcnt lgkmcnt(0)
	v_cvt_pk_bf16_f32 v84, v52, v53
	v_cvt_pk_bf16_f32 v85, v54, v55
	v_cvt_pk_bf16_f32 v86, v56, v57
	v_cvt_pk_bf16_f32 v87, v58, v59
	v_cvt_pk_bf16_f32 v88, v60, v61
	v_cvt_pk_bf16_f32 v89, v62, v63
	v_cvt_pk_bf16_f32 v90, v64, v65
	v_cvt_pk_bf16_f32 v91, v66, v67
	v_cvt_pk_bf16_f32 v92, v68, v69
	v_cvt_pk_bf16_f32 v93, v70, v71
	v_cvt_pk_bf16_f32 v94, v72, v73
	v_cvt_pk_bf16_f32 v95, v74, v75
	v_cvt_pk_bf16_f32 v96, v76, v77
	v_cvt_pk_bf16_f32 v97, v78, v79
	v_cvt_pk_bf16_f32 v98, v80, v81
	v_cvt_pk_bf16_f32 v99, v82, v83
	global_store_dwordx4 v16, v[84:87], s[98:99]
	global_store_dwordx4 v17, v[88:91], s[98:99]
	global_store_dwordx4 v18, v[92:95], s[98:99]
	global_store_dwordx4 v19, v[96:99], s[98:99]
	s_waitcnt vmcnt(23)
	ds_write_b32 v14, v20 offset:0
	ds_write_b32 v14, v21 offset:4
	ds_write_b32 v14, v22 offset:8
	ds_write_b32 v14, v23 offset:12
	s_waitcnt vmcnt(22)
	ds_write_b32 v14, v24 offset:1056
	ds_write_b32 v14, v25 offset:1060
	ds_write_b32 v14, v26 offset:1064
	ds_write_b32 v14, v27 offset:1068
	s_waitcnt vmcnt(21)
	ds_write_b32 v14, v28 offset:2112
	ds_write_b32 v14, v29 offset:2116
	ds_write_b32 v14, v30 offset:2120
	ds_write_b32 v14, v31 offset:2124
	s_waitcnt vmcnt(20)
	ds_write_b32 v14, v32 offset:3168
	ds_write_b32 v14, v33 offset:3172
	ds_write_b32 v14, v34 offset:3176
	ds_write_b32 v14, v35 offset:3180
	s_waitcnt vmcnt(19)
	ds_write_b32 v14, v36 offset:4224
	ds_write_b32 v14, v37 offset:4228
	ds_write_b32 v14, v38 offset:4232
	ds_write_b32 v14, v39 offset:4236
	s_waitcnt vmcnt(18)
	ds_write_b32 v14, v40 offset:5280
	ds_write_b32 v14, v41 offset:5284
	ds_write_b32 v14, v42 offset:5288
	ds_write_b32 v14, v43 offset:5292
	s_waitcnt vmcnt(17)
	ds_write_b32 v14, v44 offset:6336
	ds_write_b32 v14, v45 offset:6340
	ds_write_b32 v14, v46 offset:6344
	ds_write_b32 v14, v47 offset:6348
	s_waitcnt vmcnt(16)
	ds_write_b32 v14, v48 offset:7392
	ds_write_b32 v14, v49 offset:7396
	ds_write_b32 v14, v50 offset:7400
	ds_write_b32 v14, v51 offset:7404
	s_add_u32 s95, s94, 0x4000
	s_lshr_b32 vcc_lo, s95, 7
	s_and_b32 vcc_hi, s95, 0x7f
	s_lshl_b32 vcc_lo, vcc_lo, 20
	s_lshl_b32 vcc_hi, vcc_hi, 7
	s_add_u32 s96, s100, vcc_lo
	s_addc_u32 s97, s101, 0
	s_add_u32 s96, s96, vcc_hi
	s_addc_u32 s97, s97, 0
	global_load_dwordx4 v[20:23], v6, s[96:97]
	global_load_dwordx4 v[24:27], v7, s[96:97]
	global_load_dwordx4 v[28:31], v8, s[96:97]
	global_load_dwordx4 v[32:35], v9, s[96:97]
	global_load_dwordx4 v[36:39], v10, s[96:97]
	global_load_dwordx4 v[40:43], v11, s[96:97]
	global_load_dwordx4 v[44:47], v12, s[96:97]
	global_load_dwordx4 v[48:51], v13, s[96:97]
	ds_read2_b32 v[52:53], v15 offset0:0 offset1:33
	ds_read2_b32 v[54:55], v15 offset0:66 offset1:99
	ds_read2_b32 v[56:57], v15 offset0:132 offset1:165
	ds_read2_b32 v[58:59], v15 offset0:198 offset1:231
	ds_read2_b32 v[60:61], v15 offset0:8 offset1:41
	ds_read2_b32 v[62:63], v15 offset0:74 offset1:107
	ds_read2_b32 v[64:65], v15 offset0:140 offset1:173
	ds_read2_b32 v[66:67], v15 offset0:206 offset1:239
	ds_read2_b32 v[68:69], v15 offset0:16 offset1:49
	ds_read2_b32 v[70:71], v15 offset0:82 offset1:115
	ds_read2_b32 v[72:73], v15 offset0:148 offset1:181
	ds_read2_b32 v[74:75], v15 offset0:214 offset1:247
	ds_read2_b32 v[76:77], v15 offset0:24 offset1:57
	ds_read2_b32 v[78:79], v15 offset0:90 offset1:123
	ds_read2_b32 v[80:81], v15 offset0:156 offset1:189
	ds_read2_b32 v[82:83], v15 offset0:222 offset1:255
	s_add_u32 s95, s94, 0x3800
	s_lshr_b32 vcc_lo, s95, 7
	s_and_b32 vcc_hi, s95, 0x7f
	s_mul_i32 vcc_hi, vcc_hi, 0xac000
	s_lshl_b32 vcc_lo, vcc_lo, 7
	s_add_u32 s98, s66, 0x12d00000
	s_addc_u32 s99, s67, 0
	s_add_u32 s98, s98, vcc_hi
	s_addc_u32 s99, s99, 0
	s_add_u32 s98, s98, vcc_lo
	s_addc_u32 s99, s99, 0
	s_waitcnt lgkmcnt(0)
	v_cvt_pk_bf16_f32 v84, v52, v53
	v_cvt_pk_bf16_f32 v85, v54, v55
	v_cvt_pk_bf16_f32 v86, v56, v57
	v_cvt_pk_bf16_f32 v87, v58, v59
	v_cvt_pk_bf16_f32 v88, v60, v61
	v_cvt_pk_bf16_f32 v89, v62, v63
	v_cvt_pk_bf16_f32 v90, v64, v65
	v_cvt_pk_bf16_f32 v91, v66, v67
	v_cvt_pk_bf16_f32 v92, v68, v69
	v_cvt_pk_bf16_f32 v93, v70, v71
	v_cvt_pk_bf16_f32 v94, v72, v73
	v_cvt_pk_bf16_f32 v95, v74, v75
	v_cvt_pk_bf16_f32 v96, v76, v77
	v_cvt_pk_bf16_f32 v97, v78, v79
	v_cvt_pk_bf16_f32 v98, v80, v81
	v_cvt_pk_bf16_f32 v99, v82, v83
	global_store_dwordx4 v16, v[84:87], s[98:99]
	global_store_dwordx4 v17, v[88:91], s[98:99]
	global_store_dwordx4 v18, v[92:95], s[98:99]
	global_store_dwordx4 v19, v[96:99], s[98:99]
	s_waitcnt vmcnt(23)
	ds_write_b32 v14, v100 offset:0
	ds_write_b32 v14, v101 offset:4
	ds_write_b32 v14, v102 offset:8
	ds_write_b32 v14, v103 offset:12
	s_waitcnt vmcnt(22)
	ds_write_b32 v14, v104 offset:1056
	ds_write_b32 v14, v105 offset:1060
	ds_write_b32 v14, v106 offset:1064
	ds_write_b32 v14, v107 offset:1068
	s_waitcnt vmcnt(21)
	ds_write_b32 v14, v108 offset:2112
	ds_write_b32 v14, v109 offset:2116
	ds_write_b32 v14, v110 offset:2120
	ds_write_b32 v14, v111 offset:2124
	s_waitcnt vmcnt(20)
	ds_write_b32 v14, v112 offset:3168
	ds_write_b32 v14, v113 offset:3172
	ds_write_b32 v14, v114 offset:3176
	ds_write_b32 v14, v115 offset:3180
	s_waitcnt vmcnt(19)
	ds_write_b32 v14, v116 offset:4224
	ds_write_b32 v14, v117 offset:4228
	ds_write_b32 v14, v118 offset:4232
	ds_write_b32 v14, v119 offset:4236
	s_waitcnt vmcnt(18)
	ds_write_b32 v14, v120 offset:5280
	ds_write_b32 v14, v121 offset:5284
	ds_write_b32 v14, v122 offset:5288
	ds_write_b32 v14, v123 offset:5292
	s_waitcnt vmcnt(17)
	ds_write_b32 v14, v124 offset:6336
	ds_write_b32 v14, v125 offset:6340
	ds_write_b32 v14, v126 offset:6344
	ds_write_b32 v14, v127 offset:6348
	s_waitcnt vmcnt(16)
	ds_write_b32 v14, v128 offset:7392
	ds_write_b32 v14, v129 offset:7396
	ds_write_b32 v14, v130 offset:7400
	ds_write_b32 v14, v131 offset:7404
	s_add_u32 s95, s94, 0x4400
	s_lshr_b32 vcc_lo, s95, 7
	s_and_b32 vcc_hi, s95, 0x7f
	s_lshl_b32 vcc_lo, vcc_lo, 20
	s_lshl_b32 vcc_hi, vcc_hi, 7
	s_add_u32 s96, s100, vcc_lo
	s_addc_u32 s97, s101, 0
	s_add_u32 s96, s96, vcc_hi
	s_addc_u32 s97, s97, 0
	global_load_dwordx4 v[100:103], v6, s[96:97]
	global_load_dwordx4 v[104:107], v7, s[96:97]
	global_load_dwordx4 v[108:111], v8, s[96:97]
	global_load_dwordx4 v[112:115], v9, s[96:97]
	global_load_dwordx4 v[116:119], v10, s[96:97]
	global_load_dwordx4 v[120:123], v11, s[96:97]
	global_load_dwordx4 v[124:127], v12, s[96:97]
	global_load_dwordx4 v[128:131], v13, s[96:97]
	ds_read2_b32 v[52:53], v15 offset0:0 offset1:33
	ds_read2_b32 v[54:55], v15 offset0:66 offset1:99
	ds_read2_b32 v[56:57], v15 offset0:132 offset1:165
	ds_read2_b32 v[58:59], v15 offset0:198 offset1:231
	ds_read2_b32 v[60:61], v15 offset0:8 offset1:41
	ds_read2_b32 v[62:63], v15 offset0:74 offset1:107
	ds_read2_b32 v[64:65], v15 offset0:140 offset1:173
	ds_read2_b32 v[66:67], v15 offset0:206 offset1:239
	ds_read2_b32 v[68:69], v15 offset0:16 offset1:49
	ds_read2_b32 v[70:71], v15 offset0:82 offset1:115
	ds_read2_b32 v[72:73], v15 offset0:148 offset1:181
	ds_read2_b32 v[74:75], v15 offset0:214 offset1:247
	ds_read2_b32 v[76:77], v15 offset0:24 offset1:57
	ds_read2_b32 v[78:79], v15 offset0:90 offset1:123
	ds_read2_b32 v[80:81], v15 offset0:156 offset1:189
	ds_read2_b32 v[82:83], v15 offset0:222 offset1:255
	s_add_u32 s95, s94, 0x3c00
	s_lshr_b32 vcc_lo, s95, 7
	s_and_b32 vcc_hi, s95, 0x7f
	s_mul_i32 vcc_hi, vcc_hi, 0xac000
	s_lshl_b32 vcc_lo, vcc_lo, 7
	s_add_u32 s98, s66, 0x12d00000
	s_addc_u32 s99, s67, 0
	s_add_u32 s98, s98, vcc_hi
	s_addc_u32 s99, s99, 0
	s_add_u32 s98, s98, vcc_lo
	s_addc_u32 s99, s99, 0
	s_waitcnt lgkmcnt(0)
	v_cvt_pk_bf16_f32 v84, v52, v53
	v_cvt_pk_bf16_f32 v85, v54, v55
	v_cvt_pk_bf16_f32 v86, v56, v57
	v_cvt_pk_bf16_f32 v87, v58, v59
	v_cvt_pk_bf16_f32 v88, v60, v61
	v_cvt_pk_bf16_f32 v89, v62, v63
	v_cvt_pk_bf16_f32 v90, v64, v65
	v_cvt_pk_bf16_f32 v91, v66, v67
	v_cvt_pk_bf16_f32 v92, v68, v69
	v_cvt_pk_bf16_f32 v93, v70, v71
	v_cvt_pk_bf16_f32 v94, v72, v73
	v_cvt_pk_bf16_f32 v95, v74, v75
	v_cvt_pk_bf16_f32 v96, v76, v77
	v_cvt_pk_bf16_f32 v97, v78, v79
	v_cvt_pk_bf16_f32 v98, v80, v81
	v_cvt_pk_bf16_f32 v99, v82, v83
	global_store_dwordx4 v16, v[84:87], s[98:99]
	global_store_dwordx4 v17, v[88:91], s[98:99]
	global_store_dwordx4 v18, v[92:95], s[98:99]
	global_store_dwordx4 v19, v[96:99], s[98:99]
	s_waitcnt vmcnt(23)
	ds_write_b32 v14, v20 offset:0
	ds_write_b32 v14, v21 offset:4
	ds_write_b32 v14, v22 offset:8
	ds_write_b32 v14, v23 offset:12
	s_waitcnt vmcnt(22)
	ds_write_b32 v14, v24 offset:1056
	ds_write_b32 v14, v25 offset:1060
	ds_write_b32 v14, v26 offset:1064
	ds_write_b32 v14, v27 offset:1068
	s_waitcnt vmcnt(21)
	ds_write_b32 v14, v28 offset:2112
	ds_write_b32 v14, v29 offset:2116
	ds_write_b32 v14, v30 offset:2120
	ds_write_b32 v14, v31 offset:2124
	s_waitcnt vmcnt(20)
	ds_write_b32 v14, v32 offset:3168
	ds_write_b32 v14, v33 offset:3172
	ds_write_b32 v14, v34 offset:3176
	ds_write_b32 v14, v35 offset:3180
	s_waitcnt vmcnt(19)
	ds_write_b32 v14, v36 offset:4224
	ds_write_b32 v14, v37 offset:4228
	ds_write_b32 v14, v38 offset:4232
	ds_write_b32 v14, v39 offset:4236
	s_waitcnt vmcnt(18)
	ds_write_b32 v14, v40 offset:5280
	ds_write_b32 v14, v41 offset:5284
	ds_write_b32 v14, v42 offset:5288
	ds_write_b32 v14, v43 offset:5292
	s_waitcnt vmcnt(17)
	ds_write_b32 v14, v44 offset:6336
	ds_write_b32 v14, v45 offset:6340
	ds_write_b32 v14, v46 offset:6344
	ds_write_b32 v14, v47 offset:6348
	s_waitcnt vmcnt(16)
	ds_write_b32 v14, v48 offset:7392
	ds_write_b32 v14, v49 offset:7396
	ds_write_b32 v14, v50 offset:7400
	ds_write_b32 v14, v51 offset:7404
	s_add_u32 s95, s94, 0x4800
	s_lshr_b32 vcc_lo, s95, 7
	s_and_b32 vcc_hi, s95, 0x7f
	s_lshl_b32 vcc_lo, vcc_lo, 20
	s_lshl_b32 vcc_hi, vcc_hi, 7
	s_add_u32 s96, s100, vcc_lo
	s_addc_u32 s97, s101, 0
	s_add_u32 s96, s96, vcc_hi
	s_addc_u32 s97, s97, 0
	global_load_dwordx4 v[20:23], v6, s[96:97]
	global_load_dwordx4 v[24:27], v7, s[96:97]
	global_load_dwordx4 v[28:31], v8, s[96:97]
	global_load_dwordx4 v[32:35], v9, s[96:97]
	global_load_dwordx4 v[36:39], v10, s[96:97]
	global_load_dwordx4 v[40:43], v11, s[96:97]
	global_load_dwordx4 v[44:47], v12, s[96:97]
	global_load_dwordx4 v[48:51], v13, s[96:97]
	ds_read2_b32 v[52:53], v15 offset0:0 offset1:33
	ds_read2_b32 v[54:55], v15 offset0:66 offset1:99
	ds_read2_b32 v[56:57], v15 offset0:132 offset1:165
	ds_read2_b32 v[58:59], v15 offset0:198 offset1:231
	ds_read2_b32 v[60:61], v15 offset0:8 offset1:41
	ds_read2_b32 v[62:63], v15 offset0:74 offset1:107
	ds_read2_b32 v[64:65], v15 offset0:140 offset1:173
	ds_read2_b32 v[66:67], v15 offset0:206 offset1:239
	ds_read2_b32 v[68:69], v15 offset0:16 offset1:49
	ds_read2_b32 v[70:71], v15 offset0:82 offset1:115
	ds_read2_b32 v[72:73], v15 offset0:148 offset1:181
	ds_read2_b32 v[74:75], v15 offset0:214 offset1:247
	ds_read2_b32 v[76:77], v15 offset0:24 offset1:57
	ds_read2_b32 v[78:79], v15 offset0:90 offset1:123
	ds_read2_b32 v[80:81], v15 offset0:156 offset1:189
	ds_read2_b32 v[82:83], v15 offset0:222 offset1:255
	s_add_u32 s95, s94, 0x4000
	s_lshr_b32 vcc_lo, s95, 7
	s_and_b32 vcc_hi, s95, 0x7f
	s_mul_i32 vcc_hi, vcc_hi, 0xac000
	s_lshl_b32 vcc_lo, vcc_lo, 7
	s_add_u32 s98, s66, 0x12d00000
	s_addc_u32 s99, s67, 0
	s_add_u32 s98, s98, vcc_hi
	s_addc_u32 s99, s99, 0
	s_add_u32 s98, s98, vcc_lo
	s_addc_u32 s99, s99, 0
	s_waitcnt lgkmcnt(0)
	v_cvt_pk_bf16_f32 v84, v52, v53
	v_cvt_pk_bf16_f32 v85, v54, v55
	v_cvt_pk_bf16_f32 v86, v56, v57
	v_cvt_pk_bf16_f32 v87, v58, v59
	v_cvt_pk_bf16_f32 v88, v60, v61
	v_cvt_pk_bf16_f32 v89, v62, v63
	v_cvt_pk_bf16_f32 v90, v64, v65
	v_cvt_pk_bf16_f32 v91, v66, v67
	v_cvt_pk_bf16_f32 v92, v68, v69
	v_cvt_pk_bf16_f32 v93, v70, v71
	v_cvt_pk_bf16_f32 v94, v72, v73
	v_cvt_pk_bf16_f32 v95, v74, v75
	v_cvt_pk_bf16_f32 v96, v76, v77
	v_cvt_pk_bf16_f32 v97, v78, v79
	v_cvt_pk_bf16_f32 v98, v80, v81
	v_cvt_pk_bf16_f32 v99, v82, v83
	global_store_dwordx4 v16, v[84:87], s[98:99]
	global_store_dwordx4 v17, v[88:91], s[98:99]
	global_store_dwordx4 v18, v[92:95], s[98:99]
	global_store_dwordx4 v19, v[96:99], s[98:99]
	s_waitcnt vmcnt(23)
	ds_write_b32 v14, v100 offset:0
	ds_write_b32 v14, v101 offset:4
	ds_write_b32 v14, v102 offset:8
	ds_write_b32 v14, v103 offset:12
	s_waitcnt vmcnt(22)
	ds_write_b32 v14, v104 offset:1056
	ds_write_b32 v14, v105 offset:1060
	ds_write_b32 v14, v106 offset:1064
	ds_write_b32 v14, v107 offset:1068
	s_waitcnt vmcnt(21)
	ds_write_b32 v14, v108 offset:2112
	ds_write_b32 v14, v109 offset:2116
	ds_write_b32 v14, v110 offset:2120
	ds_write_b32 v14, v111 offset:2124
	s_waitcnt vmcnt(20)
	ds_write_b32 v14, v112 offset:3168
	ds_write_b32 v14, v113 offset:3172
	ds_write_b32 v14, v114 offset:3176
	ds_write_b32 v14, v115 offset:3180
	s_waitcnt vmcnt(19)
	ds_write_b32 v14, v116 offset:4224
	ds_write_b32 v14, v117 offset:4228
	ds_write_b32 v14, v118 offset:4232
	ds_write_b32 v14, v119 offset:4236
	s_waitcnt vmcnt(18)
	ds_write_b32 v14, v120 offset:5280
	ds_write_b32 v14, v121 offset:5284
	ds_write_b32 v14, v122 offset:5288
	ds_write_b32 v14, v123 offset:5292
	s_waitcnt vmcnt(17)
	ds_write_b32 v14, v124 offset:6336
	ds_write_b32 v14, v125 offset:6340
	ds_write_b32 v14, v126 offset:6344
	ds_write_b32 v14, v127 offset:6348
	s_waitcnt vmcnt(16)
	ds_write_b32 v14, v128 offset:7392
	ds_write_b32 v14, v129 offset:7396
	ds_write_b32 v14, v130 offset:7400
	ds_write_b32 v14, v131 offset:7404
	s_add_u32 s95, s94, 0x4c00
	s_lshr_b32 vcc_lo, s95, 7
	s_and_b32 vcc_hi, s95, 0x7f
	s_lshl_b32 vcc_lo, vcc_lo, 20
	s_lshl_b32 vcc_hi, vcc_hi, 7
	s_add_u32 s96, s100, vcc_lo
	s_addc_u32 s97, s101, 0
	s_add_u32 s96, s96, vcc_hi
	s_addc_u32 s97, s97, 0
	global_load_dwordx4 v[100:103], v6, s[96:97]
	global_load_dwordx4 v[104:107], v7, s[96:97]
	global_load_dwordx4 v[108:111], v8, s[96:97]
	global_load_dwordx4 v[112:115], v9, s[96:97]
	global_load_dwordx4 v[116:119], v10, s[96:97]
	global_load_dwordx4 v[120:123], v11, s[96:97]
	global_load_dwordx4 v[124:127], v12, s[96:97]
	global_load_dwordx4 v[128:131], v13, s[96:97]
	ds_read2_b32 v[52:53], v15 offset0:0 offset1:33
	ds_read2_b32 v[54:55], v15 offset0:66 offset1:99
	ds_read2_b32 v[56:57], v15 offset0:132 offset1:165
	ds_read2_b32 v[58:59], v15 offset0:198 offset1:231
	ds_read2_b32 v[60:61], v15 offset0:8 offset1:41
	ds_read2_b32 v[62:63], v15 offset0:74 offset1:107
	ds_read2_b32 v[64:65], v15 offset0:140 offset1:173
	ds_read2_b32 v[66:67], v15 offset0:206 offset1:239
	ds_read2_b32 v[68:69], v15 offset0:16 offset1:49
	ds_read2_b32 v[70:71], v15 offset0:82 offset1:115
	ds_read2_b32 v[72:73], v15 offset0:148 offset1:181
	ds_read2_b32 v[74:75], v15 offset0:214 offset1:247
	ds_read2_b32 v[76:77], v15 offset0:24 offset1:57
	ds_read2_b32 v[78:79], v15 offset0:90 offset1:123
	ds_read2_b32 v[80:81], v15 offset0:156 offset1:189
	ds_read2_b32 v[82:83], v15 offset0:222 offset1:255
	s_add_u32 s95, s94, 0x4400
	s_lshr_b32 vcc_lo, s95, 7
	s_and_b32 vcc_hi, s95, 0x7f
	s_mul_i32 vcc_hi, vcc_hi, 0xac000
	s_lshl_b32 vcc_lo, vcc_lo, 7
	s_add_u32 s98, s66, 0x12d00000
	s_addc_u32 s99, s67, 0
	s_add_u32 s98, s98, vcc_hi
	s_addc_u32 s99, s99, 0
	s_add_u32 s98, s98, vcc_lo
	s_addc_u32 s99, s99, 0
	s_waitcnt lgkmcnt(0)
	v_cvt_pk_bf16_f32 v84, v52, v53
	v_cvt_pk_bf16_f32 v85, v54, v55
	v_cvt_pk_bf16_f32 v86, v56, v57
	v_cvt_pk_bf16_f32 v87, v58, v59
	v_cvt_pk_bf16_f32 v88, v60, v61
	v_cvt_pk_bf16_f32 v89, v62, v63
	v_cvt_pk_bf16_f32 v90, v64, v65
	v_cvt_pk_bf16_f32 v91, v66, v67
	v_cvt_pk_bf16_f32 v92, v68, v69
	v_cvt_pk_bf16_f32 v93, v70, v71
	v_cvt_pk_bf16_f32 v94, v72, v73
	v_cvt_pk_bf16_f32 v95, v74, v75
	v_cvt_pk_bf16_f32 v96, v76, v77
	v_cvt_pk_bf16_f32 v97, v78, v79
	v_cvt_pk_bf16_f32 v98, v80, v81
	v_cvt_pk_bf16_f32 v99, v82, v83
	global_store_dwordx4 v16, v[84:87], s[98:99]
	global_store_dwordx4 v17, v[88:91], s[98:99]
	global_store_dwordx4 v18, v[92:95], s[98:99]
	global_store_dwordx4 v19, v[96:99], s[98:99]
	s_waitcnt vmcnt(23)
	ds_write_b32 v14, v20 offset:0
	ds_write_b32 v14, v21 offset:4
	ds_write_b32 v14, v22 offset:8
	ds_write_b32 v14, v23 offset:12
	s_waitcnt vmcnt(22)
	ds_write_b32 v14, v24 offset:1056
	ds_write_b32 v14, v25 offset:1060
	ds_write_b32 v14, v26 offset:1064
	ds_write_b32 v14, v27 offset:1068
	s_waitcnt vmcnt(21)
	ds_write_b32 v14, v28 offset:2112
	ds_write_b32 v14, v29 offset:2116
	ds_write_b32 v14, v30 offset:2120
	ds_write_b32 v14, v31 offset:2124
	s_waitcnt vmcnt(20)
	ds_write_b32 v14, v32 offset:3168
	ds_write_b32 v14, v33 offset:3172
	ds_write_b32 v14, v34 offset:3176
	ds_write_b32 v14, v35 offset:3180
	s_waitcnt vmcnt(19)
	ds_write_b32 v14, v36 offset:4224
	ds_write_b32 v14, v37 offset:4228
	ds_write_b32 v14, v38 offset:4232
	ds_write_b32 v14, v39 offset:4236
	s_waitcnt vmcnt(18)
	ds_write_b32 v14, v40 offset:5280
	ds_write_b32 v14, v41 offset:5284
	ds_write_b32 v14, v42 offset:5288
	ds_write_b32 v14, v43 offset:5292
	s_waitcnt vmcnt(17)
	ds_write_b32 v14, v44 offset:6336
	ds_write_b32 v14, v45 offset:6340
	ds_write_b32 v14, v46 offset:6344
	ds_write_b32 v14, v47 offset:6348
	s_waitcnt vmcnt(16)
	ds_write_b32 v14, v48 offset:7392
	ds_write_b32 v14, v49 offset:7396
	ds_write_b32 v14, v50 offset:7400
	ds_write_b32 v14, v51 offset:7404
	ds_read2_b32 v[52:53], v15 offset0:0 offset1:33
	ds_read2_b32 v[54:55], v15 offset0:66 offset1:99
	ds_read2_b32 v[56:57], v15 offset0:132 offset1:165
	ds_read2_b32 v[58:59], v15 offset0:198 offset1:231
	ds_read2_b32 v[60:61], v15 offset0:8 offset1:41
	ds_read2_b32 v[62:63], v15 offset0:74 offset1:107
	ds_read2_b32 v[64:65], v15 offset0:140 offset1:173
	ds_read2_b32 v[66:67], v15 offset0:206 offset1:239
	ds_read2_b32 v[68:69], v15 offset0:16 offset1:49
	ds_read2_b32 v[70:71], v15 offset0:82 offset1:115
	ds_read2_b32 v[72:73], v15 offset0:148 offset1:181
	ds_read2_b32 v[74:75], v15 offset0:214 offset1:247
	ds_read2_b32 v[76:77], v15 offset0:24 offset1:57
	ds_read2_b32 v[78:79], v15 offset0:90 offset1:123
	ds_read2_b32 v[80:81], v15 offset0:156 offset1:189
	ds_read2_b32 v[82:83], v15 offset0:222 offset1:255
	s_add_u32 s95, s94, 0x4800
	s_lshr_b32 vcc_lo, s95, 7
	s_and_b32 vcc_hi, s95, 0x7f
	s_mul_i32 vcc_hi, vcc_hi, 0xac000
	s_lshl_b32 vcc_lo, vcc_lo, 7
	s_add_u32 s98, s66, 0x12d00000
	s_addc_u32 s99, s67, 0
	s_add_u32 s98, s98, vcc_hi
	s_addc_u32 s99, s99, 0
	s_add_u32 s98, s98, vcc_lo
	s_addc_u32 s99, s99, 0
	s_waitcnt lgkmcnt(0)
	v_cvt_pk_bf16_f32 v84, v52, v53
	v_cvt_pk_bf16_f32 v85, v54, v55
	v_cvt_pk_bf16_f32 v86, v56, v57
	v_cvt_pk_bf16_f32 v87, v58, v59
	v_cvt_pk_bf16_f32 v88, v60, v61
	v_cvt_pk_bf16_f32 v89, v62, v63
	v_cvt_pk_bf16_f32 v90, v64, v65
	v_cvt_pk_bf16_f32 v91, v66, v67
	v_cvt_pk_bf16_f32 v92, v68, v69
	v_cvt_pk_bf16_f32 v93, v70, v71
	v_cvt_pk_bf16_f32 v94, v72, v73
	v_cvt_pk_bf16_f32 v95, v74, v75
	v_cvt_pk_bf16_f32 v96, v76, v77
	v_cvt_pk_bf16_f32 v97, v78, v79
	v_cvt_pk_bf16_f32 v98, v80, v81
	v_cvt_pk_bf16_f32 v99, v82, v83
	global_store_dwordx4 v16, v[84:87], s[98:99]
	global_store_dwordx4 v17, v[88:91], s[98:99]
	global_store_dwordx4 v18, v[92:95], s[98:99]
	global_store_dwordx4 v19, v[96:99], s[98:99]
	s_waitcnt vmcnt(15)
	ds_write_b32 v14, v100 offset:0
	ds_write_b32 v14, v101 offset:4
	ds_write_b32 v14, v102 offset:8
	ds_write_b32 v14, v103 offset:12
	s_waitcnt vmcnt(14)
	ds_write_b32 v14, v104 offset:1056
	ds_write_b32 v14, v105 offset:1060
	ds_write_b32 v14, v106 offset:1064
	ds_write_b32 v14, v107 offset:1068
	s_waitcnt vmcnt(13)
	ds_write_b32 v14, v108 offset:2112
	ds_write_b32 v14, v109 offset:2116
	ds_write_b32 v14, v110 offset:2120
	ds_write_b32 v14, v111 offset:2124
	s_waitcnt vmcnt(12)
	ds_write_b32 v14, v112 offset:3168
	ds_write_b32 v14, v113 offset:3172
	ds_write_b32 v14, v114 offset:3176
	ds_write_b32 v14, v115 offset:3180
	s_waitcnt vmcnt(11)
	ds_write_b32 v14, v116 offset:4224
	ds_write_b32 v14, v117 offset:4228
	ds_write_b32 v14, v118 offset:4232
	ds_write_b32 v14, v119 offset:4236
	s_waitcnt vmcnt(10)
	ds_write_b32 v14, v120 offset:5280
	ds_write_b32 v14, v121 offset:5284
	ds_write_b32 v14, v122 offset:5288
	ds_write_b32 v14, v123 offset:5292
	s_waitcnt vmcnt(9)
	ds_write_b32 v14, v124 offset:6336
	ds_write_b32 v14, v125 offset:6340
	ds_write_b32 v14, v126 offset:6344
	ds_write_b32 v14, v127 offset:6348
	s_waitcnt vmcnt(8)
	ds_write_b32 v14, v128 offset:7392
	ds_write_b32 v14, v129 offset:7396
	ds_write_b32 v14, v130 offset:7400
	ds_write_b32 v14, v131 offset:7404
	ds_read2_b32 v[52:53], v15 offset0:0 offset1:33
	ds_read2_b32 v[54:55], v15 offset0:66 offset1:99
	ds_read2_b32 v[56:57], v15 offset0:132 offset1:165
	ds_read2_b32 v[58:59], v15 offset0:198 offset1:231
	ds_read2_b32 v[60:61], v15 offset0:8 offset1:41
	ds_read2_b32 v[62:63], v15 offset0:74 offset1:107
	ds_read2_b32 v[64:65], v15 offset0:140 offset1:173
	ds_read2_b32 v[66:67], v15 offset0:206 offset1:239
	ds_read2_b32 v[68:69], v15 offset0:16 offset1:49
	ds_read2_b32 v[70:71], v15 offset0:82 offset1:115
	ds_read2_b32 v[72:73], v15 offset0:148 offset1:181
	ds_read2_b32 v[74:75], v15 offset0:214 offset1:247
	ds_read2_b32 v[76:77], v15 offset0:24 offset1:57
	ds_read2_b32 v[78:79], v15 offset0:90 offset1:123
	ds_read2_b32 v[80:81], v15 offset0:156 offset1:189
	ds_read2_b32 v[82:83], v15 offset0:222 offset1:255
	s_add_u32 s95, s94, 0x4c00
	s_lshr_b32 vcc_lo, s95, 7
	s_and_b32 vcc_hi, s95, 0x7f
	s_mul_i32 vcc_hi, vcc_hi, 0xac000
	s_lshl_b32 vcc_lo, vcc_lo, 7
	s_add_u32 s98, s66, 0x12d00000
	s_addc_u32 s99, s67, 0
	s_add_u32 s98, s98, vcc_hi
	s_addc_u32 s99, s99, 0
	s_add_u32 s98, s98, vcc_lo
	s_addc_u32 s99, s99, 0
	s_waitcnt lgkmcnt(0)
	v_cvt_pk_bf16_f32 v84, v52, v53
	v_cvt_pk_bf16_f32 v85, v54, v55
	v_cvt_pk_bf16_f32 v86, v56, v57
	v_cvt_pk_bf16_f32 v87, v58, v59
	v_cvt_pk_bf16_f32 v88, v60, v61
	v_cvt_pk_bf16_f32 v89, v62, v63
	v_cvt_pk_bf16_f32 v90, v64, v65
	v_cvt_pk_bf16_f32 v91, v66, v67
	v_cvt_pk_bf16_f32 v92, v68, v69
	v_cvt_pk_bf16_f32 v93, v70, v71
	v_cvt_pk_bf16_f32 v94, v72, v73
	v_cvt_pk_bf16_f32 v95, v74, v75
	v_cvt_pk_bf16_f32 v96, v76, v77
	v_cvt_pk_bf16_f32 v97, v78, v79
	v_cvt_pk_bf16_f32 v98, v80, v81
	v_cvt_pk_bf16_f32 v99, v82, v83
	global_store_dwordx4 v16, v[84:87], s[98:99]
	global_store_dwordx4 v17, v[88:91], s[98:99]
	global_store_dwordx4 v18, v[92:95], s[98:99]
	global_store_dwordx4 v19, v[96:99], s[98:99]
